# DA attention: ping-pong halves (2 barriers/tile, waves 4-7 lag), segment priorities, deep K/V fragment prefetch
# speedup vs baseline: 1.0166x; 1.0166x over previous
; __device__ __forceinline__ int v_rd_base(int lane) { return ((lane & 3) << 3) | (((lane >> 2) & 3) << 6) | (((lane >> 4) & 1) << 5) | (((lane >> 5) & 1) << 8); }
; #define DPUB() do { asm volatile("s_waitcnt vmcnt(0)" ::: "memory"); __syncthreads(); } while (0)
; __device__ __forceinline__ void unit_body_da(const Unit& U, char* lds) {
;   int tid = threadIdx.x; asm volatile("" : "+v"(tid)); const int wid = __builtin_amdgcn_readfirstlane(tid >> 6), lane = tid & 63, r32 = lane & 31, hi = lane >> 5;
;   char* V_lds = lds; char* K_lds = lds + 2 * DA_VB;
;   float* ws = (float*)(lds + DA_WS_OFF) + wid * 64; float* li_l = ws; float* al_l = ws + 32;
;   float m_reg = -1e30f, l_reg = 0; f32x16 o[8] = {}; bf16x8 qr[8];
;   const bf16_t* Qw = U.Q + (long)(wid * QBLK + r32) * LDP + hi * 8;
; #pragma unroll
;   for (int d0 = 0; d0 < 8; ++d0) qr[d0] = ld8(Qw + d0 * 16);
;   const int vb0 = (int)(uintptr_t)V_lds + v_rd_base(lane);
;   const int ka0 = (int)(uintptr_t)K_lds + KSWZ(r32, hi * 16);
;   constexpr float C = SCALE * 1.4426950408889634f;
;   unsigned koff[2], voff[2][2];
; #pragma unroll
;   for (int i = 0; i < 2; ++i) { const int ob = (2 * wid + i) * 1024 + lane * 16;
;     { const int row = ob >> 8, cpos = (ob >> 4) & 15, c = cpos ^ (row & 7); koff[i] = (unsigned)(row * LDP + c * 8); }
;     { const int st = ob >> 9, kk = (st >> 2) * 8 + ((ob >> 6) & 7), c = (st & 3) * 32 + ((ob >> 1) & 31), k = (kk & ~0xC) | ((kk & 4) << 1) | ((kk & 8) >> 1);
;       voff[0][i] = (unsigned)(k * LDP + c); voff[1][i] = (unsigned)(k * LDP + 128 + c); } }
;   typedef __attribute__((address_space(3))) unsigned lds_u32;
;     ...
;   const int NT = U.nt;
;   DDMA(0, 0); DPUB();
;   for (int j = 0; j < NT; j += 2) {
.LBB0_426:
	s_cbranch_execz .LBB0_370
	v_mov_b32_e32 v8, v210
	v_mov_b64_e32 v[2:3], s[58:59]
	v_readfirstlane_b32 s3, v8
	s_ashr_i32 s6, s3, 6
	s_and_b32 s3, s3, 0x3fffffc0
	s_lshl_b32 s3, s3, 2
	v_and_b32_e32 v234, 31, v8
	s_add_i32 s24, s3, 0
	s_lshl_b32 s64, s6, 5
	v_bfe_u32 v233, v8, 5, 1
	s_add_i32 s24, s24, 0x18000
	v_or_b32_e32 v0, s64, v234
	s_add_i32 s67, 0, 0x10000
	v_mad_i64_i32 v[2:3], s[4:5], v0, s96, v[2:3]
	v_lshlrev_b32_e32 v212, 4, v233
	v_mov_b32_e32 v213, v1
	s_cmp_lg_u32 s67, -1
	v_lshl_add_u64 v[2:3], v[2:3], 0, v[212:213]
	s_cselect_b32 s3, s67, 0
	s_lshl_b32 s25, s6, 11
	global_load_dwordx4 v[162:165], v[2:3], off
	global_load_dwordx4 v[166:169], v[2:3], off offset:32
	global_load_dwordx4 v[170:173], v[2:3], off offset:64
	global_load_dwordx4 v[174:177], v[2:3], off offset:96
	global_load_dwordx4 v[178:181], v[2:3], off offset:128
	global_load_dwordx4 v[182:185], v[2:3], off offset:160
	global_load_dwordx4 v[186:189], v[2:3], off offset:192
	global_load_dwordx4 v[190:193], v[2:3], off offset:224
	s_ashr_i32 s4, s25, 8
	v_lshrrev_b32_e32 v2, 1, v8
	v_and_b32_e32 v9, 63, v8
	v_bfe_u32 v0, v8, 2, 2
	s_and_b32 s5, s4, 0xfffff0
	v_and_b32_e32 v2, 8, v2
	v_lshlrev_b32_e32 v12, 4, v9
	s_lshr_b32 s4, s4, 1
	v_or3_b32 v0, v2, v0, s5
	v_and_or_b32 v0, s4, 4, v0
	v_or_b32_e32 v5, 0x400, v12
	v_mul_i32_i24_e32 v13, 0x1800, v0
	v_or_b32_e32 v0, s25, v12
	v_or_b32_e32 v4, s25, v5
	v_and_b32_e32 v3, 15, v8
	v_ashrrev_i32_e32 v0, 8, v0
	v_ashrrev_i32_e32 v4, 8, v4
	v_bitop3_b32 v2, v0, v3, 3 bitop3:0x6c
	v_bitop3_b32 v3, v4, v3, 7 bitop3:0x6c
	v_mul_i32_i24_e32 v4, 0x1800, v4
	v_lshlrev_b32_e32 v10, 3, v9
	v_mul_i32_i24_e32 v0, 0x1800, v0
	v_lshl_or_b32 v4, v3, 3, v4
	v_lshrrev_b32_e32 v3, 4, v5
	v_and_b32_e32 v11, 24, v10
	v_lshl_or_b32 v0, v2, 3, v0
	v_and_b32_e32 v14, 32, v8
	v_and_b32_e32 v3, 0x60, v3
	s_add_i32 s28, s67, s25
	v_or3_b32 v2, v11, v14, v13
	v_or3_b32 v6, v11, v3, v13
	v_lshl_add_u64 v[214:215], v[0:1], 1, s[46:47]
	s_mov_b32 m0, s28
	v_mov_b32_e32 v3, v1
	s_add_i32 s29, s25, 0
	global_load_lds_dwordx4 v[214:215], off
	v_lshl_add_u64 v[2:3], v[2:3], 1, s[22:23]
	s_mov_b32 m0, s29
	s_mov_b64 s[4:5], 0x100
	s_add_i32 s65, s29, 0x4000
	s_or_b32 s66, s25, 0x400
	global_load_lds_dwordx4 v[2:3], off
	v_lshl_add_u64 v[2:3], v[2:3], 0, s[4:5]
	s_mov_b32 m0, s65
	v_mov_b32_e32 v5, v1
	s_add_i32 s67, s67, s66
	global_load_lds_dwordx4 v[2:3], off
	v_lshl_add_u64 v[216:217], v[4:5], 1, s[46:47]
	s_mov_b32 m0, s67
	v_mov_b32_e32 v7, v1
	s_add_i32 s68, s29, 0x400
	global_load_lds_dwordx4 v[216:217], off
	v_lshl_add_u64 v[2:3], v[6:7], 1, s[22:23]
	s_mov_b32 m0, s68
	s_add_i32 s69, s29, 0x4400
	global_load_lds_dwordx4 v[2:3], off
	v_lshl_add_u64 v[2:3], v[2:3], 0, s[4:5]
	s_mov_b32 m0, s69
	v_lshlrev_b32_e32 v0, 1, v8
	global_load_lds_dwordx4 v[2:3], off
	v_and_b32_e32 v0, 32, v0
	v_and_or_b32 v0, v12, s97, v0
	v_and_b32_e32 v2, 0x100, v10
	s_cmp_lg_u32 0, -1
	v_or3_b32 v0, v0, v2, v11
	v_bitop3_b32 v3, v233, v8, 7 bitop3:0x78
	s_cselect_b32 s6, 0, 0
	v_lshlrev_b32_e32 v2, 8, v234
	v_lshlrev_b32_e32 v3, 4, v3
	v_add_u32_e32 v213, s6, v0
	s_add_i32 s6, s6, 0x8000
	v_add3_u32 v235, v2, s3, v3
	v_add_u32_e32 v244, s6, v0
	v_or3_b32 v0, v13, v14, v11
	s_movk_i32 s3, 0x60
	v_lshl_add_u64 v[218:219], v[0:1], 1, s[22:23]
	v_bitop3_b32 v0, v9, s3, 64 bitop3:0xc8
	v_or3_b32 v0, v13, v0, v11
	v_mov_b32_e32 v14, v1
	v_mov_b32_e32 v15, v1
	s_waitcnt vmcnt(0)
	v_cmp_gt_u32_e64 s[4:5], 32, v9
	v_lshl_add_u64 v[220:221], v[0:1], 1, s[22:23]
	v_mov_b32_e32 v0, v1
	v_mov_b32_e32 v2, v1
	v_mov_b32_e32 v3, v1
	v_mov_b32_e32 v4, v1
	v_mov_b32_e32 v6, v1
	v_mov_b32_e32 v8, v1
	v_mov_b32_e32 v9, v1
	v_mov_b32_e32 v10, v1
	v_mov_b32_e32 v11, v1
	v_mov_b32_e32 v12, v1
	v_mov_b32_e32 v13, v1
	v_mov_b64_e32 v[128:129], v[14:15]
	v_mov_b64_e32 v[112:113], v[14:15]
	v_mov_b64_e32 v[96:97], v[14:15]
	v_mov_b64_e32 v[80:81], v[14:15]
	v_mov_b64_e32 v[64:65], v[14:15]
	v_mov_b64_e32 v[48:49], v[14:15]
	v_mov_b64_e32 v[32:33], v[14:15]
	v_mov_b64_e32 v[126:127], v[12:13]
	v_mov_b64_e32 v[124:125], v[10:11]
	v_mov_b64_e32 v[122:123], v[8:9]
	v_mov_b64_e32 v[120:121], v[6:7]
	v_mov_b64_e32 v[118:119], v[4:5]
	v_mov_b64_e32 v[116:117], v[2:3]
	v_mov_b64_e32 v[114:115], v[0:1]
	v_mov_b64_e32 v[110:111], v[12:13]
	v_mov_b64_e32 v[108:109], v[10:11]
	v_mov_b64_e32 v[106:107], v[8:9]
	v_mov_b64_e32 v[104:105], v[6:7]
	v_mov_b64_e32 v[102:103], v[4:5]
	v_mov_b64_e32 v[100:101], v[2:3]
	v_mov_b64_e32 v[98:99], v[0:1]
	v_mov_b64_e32 v[94:95], v[12:13]
	v_mov_b64_e32 v[92:93], v[10:11]
	v_mov_b64_e32 v[90:91], v[8:9]
	v_mov_b64_e32 v[88:89], v[6:7]
	v_mov_b64_e32 v[86:87], v[4:5]
	v_mov_b64_e32 v[84:85], v[2:3]
	v_mov_b64_e32 v[82:83], v[0:1]
	v_mov_b64_e32 v[78:79], v[12:13]
	v_mov_b64_e32 v[76:77], v[10:11]
	v_mov_b64_e32 v[74:75], v[8:9]
	v_mov_b64_e32 v[72:73], v[6:7]
	v_mov_b64_e32 v[70:71], v[4:5]
	v_mov_b64_e32 v[68:69], v[2:3]
	v_mov_b64_e32 v[66:67], v[0:1]
	v_mov_b64_e32 v[62:63], v[12:13]
	v_mov_b64_e32 v[60:61], v[10:11]
	v_mov_b64_e32 v[58:59], v[8:9]
	v_mov_b64_e32 v[56:57], v[6:7]
	v_mov_b64_e32 v[54:55], v[4:5]
	v_mov_b64_e32 v[52:53], v[2:3]
	v_mov_b64_e32 v[50:51], v[0:1]
	v_mov_b64_e32 v[46:47], v[12:13]
	v_mov_b64_e32 v[44:45], v[10:11]
	v_mov_b64_e32 v[42:43], v[8:9]
	v_mov_b64_e32 v[40:41], v[6:7]
	v_mov_b64_e32 v[38:39], v[4:5]
	v_mov_b64_e32 v[36:37], v[2:3]
	v_mov_b64_e32 v[34:35], v[0:1]
	v_mov_b64_e32 v[30:31], v[12:13]
	v_mov_b64_e32 v[28:29], v[10:11]
	v_mov_b64_e32 v[26:27], v[8:9]
	v_mov_b64_e32 v[24:25], v[6:7]
	v_mov_b64_e32 v[22:23], v[4:5]
	v_mov_b64_e32 v[20:21], v[2:3]
	v_mov_b64_e32 v[18:19], v[0:1]
	v_mov_b64_e32 v[16:17], v[14:15]
	s_mov_b32 s80, 2
	v_xor_b32_e32 v236, 32, v235
	v_xor_b32_e32 v238, 64, v235
	v_xor_b32_e32 v239, 0x60, v235
	v_xor_b32_e32 v240, 0x80, v235
	v_xor_b32_e32 v241, 0xa0, v235
	v_xor_b32_e32 v242, 0xc0, v235
	v_xor_b32_e32 v243, 0xe0, v235
	v_lshl_add_u32 v237, v234, 2, s24
	v_mov_b32_e32 v245, 0
	v_mov_b32_e32 v246, 0xf149f2ca
	s_mov_b64 s[22:23], 0
	v_mov_b64_e32 v[14:15], v[12:13]
	v_mov_b64_e32 v[12:13], v[10:11]
	v_mov_b64_e32 v[10:11], v[8:9]
	v_mov_b64_e32 v[8:9], v[6:7]
	v_mov_b64_e32 v[6:7], v[4:5]
	v_mov_b64_e32 v[4:5], v[2:3]
	v_mov_b64_e32 v[2:3], v[0:1]
	s_waitcnt vmcnt(0) lgkmcnt(0)
	s_barrier
	s_cmp_lt_u32 s25, 0x2000
	s_cbranch_scc1 .Lda_l0_lead_in
	s_barrier
; __device__ __forceinline__ void partialSM(f32x16& p0, f32x16& p1, float& m_reg, float& mn, float& alpha) {
;     ...
;   float mnC = -mn * C;
; #pragma unroll
;   for (int r = 0; r < 16; ++r) p0[r] = fmaf(p0[r], C, mnC);
; #pragma unroll
;   for (int r = 0; r < 16; ++r) p1[r] = fmaf(p1[r], C, mnC);
; #pragma unroll
;   for (int r = 0; r < 16; ++r) p0[r] = __builtin_amdgcn_exp2f(p0[r]);
; }
; __device__ __forceinline__ void finishSM(f32x16& p0, f32x16& p1, float alpha, float& l_reg, bf16x8& pa0, bf16x8& pa1, bf16x8& pa2, bf16x8& pa3) {
; #pragma unroll
;   for (int r = 0; r < 16; ++r) p1[r] = __builtin_amdgcn_exp2f(p1[r]);
;   float ps = 0;
; #pragma unroll
;   for (int r = 0; r < 16; ++r) ps += p0[r];
; #pragma unroll
;   for (int r = 0; r < 16; ++r) ps += p1[r];
;   { auto rr = __builtin_amdgcn_permlane32_swap(__float_as_uint(ps), __float_as_uint(ps), false, false);
;     ps = __uint_as_float(rr[0]) + __uint_as_float(rr[1]); }
;   l_reg = l_reg * alpha + ps;
.Lda_l0_lead_in:
	s_branch .LBB0_430
.LBB0_428:
	s_or_b64 exec, exec, s[58:59]
	s_waitcnt lgkmcnt(0)
	v_add_u32_e32 v194, s24, v212
	ds_read_b128 v[206:209], v194 offset:224
	ds_read_b128 v[202:205], v194 offset:192
	ds_read_b128 v[198:201], v194 offset:160
	ds_read_b128 v[194:197], v194 offset:128
	s_waitcnt lgkmcnt(0)
	v_pk_mul_f32 v[126:127], v[126:127], v[206:207]
	v_pk_mul_f32 v[122:123], v[122:123], v[202:203]
	v_pk_mul_f32 v[118:119], v[118:119], v[198:199]
	v_pk_mul_f32 v[128:129], v[128:129], v[208:209]
	v_pk_mul_f32 v[124:125], v[124:125], v[204:205]
	v_pk_mul_f32 v[120:121], v[120:121], v[200:201]
	v_pk_mul_f32 v[116:117], v[116:117], v[196:197]
	v_pk_mul_f32 v[114:115], v[114:115], v[194:195]
	v_pk_mul_f32 v[110:111], v[110:111], v[206:207]
	v_pk_mul_f32 v[106:107], v[106:107], v[202:203]
	v_pk_mul_f32 v[102:103], v[102:103], v[198:199]
	v_pk_mul_f32 v[112:113], v[112:113], v[208:209]
	v_pk_mul_f32 v[108:109], v[108:109], v[204:205]
	v_pk_mul_f32 v[104:105], v[104:105], v[200:201]
	v_pk_mul_f32 v[100:101], v[100:101], v[196:197]
	v_pk_mul_f32 v[98:99], v[98:99], v[194:195]
	v_pk_mul_f32 v[94:95], v[94:95], v[206:207]
	v_pk_mul_f32 v[90:91], v[90:91], v[202:203]
	v_pk_mul_f32 v[86:87], v[86:87], v[198:199]
	v_pk_mul_f32 v[96:97], v[96:97], v[208:209]
	v_pk_mul_f32 v[92:93], v[92:93], v[204:205]
	v_pk_mul_f32 v[88:89], v[88:89], v[200:201]
	v_pk_mul_f32 v[84:85], v[84:85], v[196:197]
	v_pk_mul_f32 v[82:83], v[82:83], v[194:195]
	v_pk_mul_f32 v[78:79], v[78:79], v[206:207]
	v_pk_mul_f32 v[74:75], v[74:75], v[202:203]
	v_pk_mul_f32 v[70:71], v[70:71], v[198:199]
	v_pk_mul_f32 v[80:81], v[80:81], v[208:209]
	v_pk_mul_f32 v[76:77], v[76:77], v[204:205]
	v_pk_mul_f32 v[72:73], v[72:73], v[200:201]
	v_pk_mul_f32 v[68:69], v[68:69], v[196:197]
	v_pk_mul_f32 v[66:67], v[66:67], v[194:195]
	v_pk_mul_f32 v[62:63], v[62:63], v[206:207]
	v_pk_mul_f32 v[58:59], v[58:59], v[202:203]
	v_pk_mul_f32 v[54:55], v[54:55], v[198:199]
	v_pk_mul_f32 v[64:65], v[64:65], v[208:209]
	v_pk_mul_f32 v[60:61], v[60:61], v[204:205]
	v_pk_mul_f32 v[56:57], v[56:57], v[200:201]
	v_pk_mul_f32 v[52:53], v[52:53], v[196:197]
	v_pk_mul_f32 v[50:51], v[50:51], v[194:195]
	v_pk_mul_f32 v[46:47], v[46:47], v[206:207]
	v_pk_mul_f32 v[42:43], v[42:43], v[202:203]
	v_pk_mul_f32 v[38:39], v[38:39], v[198:199]
	v_pk_mul_f32 v[48:49], v[48:49], v[208:209]
	v_pk_mul_f32 v[44:45], v[44:45], v[204:205]
	v_pk_mul_f32 v[40:41], v[40:41], v[200:201]
	v_pk_mul_f32 v[36:37], v[36:37], v[196:197]
	v_pk_mul_f32 v[34:35], v[34:35], v[194:195]
	v_pk_mul_f32 v[30:31], v[30:31], v[206:207]
	v_pk_mul_f32 v[26:27], v[26:27], v[202:203]
	v_pk_mul_f32 v[22:23], v[22:23], v[198:199]
	v_pk_mul_f32 v[32:33], v[32:33], v[208:209]
	v_pk_mul_f32 v[28:29], v[28:29], v[204:205]
	v_pk_mul_f32 v[24:25], v[24:25], v[200:201]
	v_pk_mul_f32 v[20:21], v[20:21], v[196:197]
	v_pk_mul_f32 v[18:19], v[18:19], v[194:195]
	v_pk_mul_f32 v[14:15], v[14:15], v[206:207]
	v_pk_mul_f32 v[10:11], v[10:11], v[202:203]
	v_pk_mul_f32 v[6:7], v[6:7], v[198:199]
	v_pk_mul_f32 v[16:17], v[16:17], v[208:209]
	v_pk_mul_f32 v[12:13], v[12:13], v[204:205]
	v_pk_mul_f32 v[8:9], v[8:9], v[200:201]
	v_pk_mul_f32 v[4:5], v[4:5], v[196:197]
	v_pk_mul_f32 v[2:3], v[2:3], v[194:195]
.LBB0_429:
	v_cndmask_b32_e64 v246, v223, v246, s[6:7]
	v_mul_f32_e32 v194, 0xbe0293ee, v246
	v_fmamk_f32 v146, v146, 0x3e0293ee, v194
	v_fmamk_f32 v147, v147, 0x3e0293ee, v194
	v_fmamk_f32 v148, v148, 0x3e0293ee, v194
	v_fmamk_f32 v149, v149, 0x3e0293ee, v194
	v_fmamk_f32 v150, v150, 0x3e0293ee, v194
	v_fmamk_f32 v151, v151, 0x3e0293ee, v194
	v_fmamk_f32 v152, v152, 0x3e0293ee, v194
	v_fmamk_f32 v153, v153, 0x3e0293ee, v194
	v_fmamk_f32 v154, v154, 0x3e0293ee, v194
	v_fmamk_f32 v155, v155, 0x3e0293ee, v194
	v_fmamk_f32 v156, v156, 0x3e0293ee, v194
	v_fmamk_f32 v157, v157, 0x3e0293ee, v194
	v_fmamk_f32 v158, v158, 0x3e0293ee, v194
	v_fmamk_f32 v159, v159, 0x3e0293ee, v194
	v_fmamk_f32 v160, v160, 0x3e0293ee, v194
	v_fmamk_f32 v161, v161, 0x3e0293ee, v194
	v_fmamk_f32 v130, v130, 0x3e0293ee, v194
	v_fmamk_f32 v131, v131, 0x3e0293ee, v194
	v_fmamk_f32 v132, v132, 0x3e0293ee, v194
	v_fmamk_f32 v133, v133, 0x3e0293ee, v194
	v_fmamk_f32 v134, v134, 0x3e0293ee, v194
	v_fmamk_f32 v135, v135, 0x3e0293ee, v194
	v_fmamk_f32 v136, v136, 0x3e0293ee, v194
	v_fmamk_f32 v137, v137, 0x3e0293ee, v194
	v_fmamk_f32 v138, v138, 0x3e0293ee, v194
	v_fmamk_f32 v139, v139, 0x3e0293ee, v194
	v_fmamk_f32 v140, v140, 0x3e0293ee, v194
	v_fmamk_f32 v141, v141, 0x3e0293ee, v194
	v_fmamk_f32 v142, v142, 0x3e0293ee, v194
	v_fmamk_f32 v143, v143, 0x3e0293ee, v194
	v_fmamk_f32 v144, v144, 0x3e0293ee, v194
	v_fmac_f32_e32 v194, 0x3e0293ee, v145
	v_exp_f32_e32 v145, v146
	v_exp_f32_e32 v146, v147
	v_exp_f32_e32 v147, v148
	v_exp_f32_e32 v148, v149
	v_exp_f32_e32 v149, v150
	v_exp_f32_e32 v150, v151
	v_exp_f32_e32 v151, v152
	v_exp_f32_e32 v152, v153
	v_exp_f32_e32 v153, v154
	v_exp_f32_e32 v154, v155
	v_exp_f32_e32 v155, v156
	v_exp_f32_e32 v156, v157
	v_exp_f32_e32 v157, v158
	v_exp_f32_e32 v158, v159
	v_exp_f32_e32 v159, v160
	v_exp_f32_e32 v160, v161
	v_add_f32_e32 v161, v247, v248
	v_fmac_f32_e32 v161, v245, v0
	v_exp_f32_e32 v0, v130
	v_add_f32_e32 v130, 0, v145
	v_add_f32_e32 v130, v146, v130
	v_add_f32_e32 v130, v147, v130
	v_add_f32_e32 v130, v148, v130
	v_add_f32_e32 v130, v149, v130
	v_add_f32_e32 v130, v150, v130
	v_add_f32_e32 v130, v151, v130
	v_add_f32_e32 v130, v152, v130
	v_add_f32_e32 v130, v153, v130
	v_add_f32_e32 v130, v154, v130
	v_add_f32_e32 v130, v155, v130
	v_add_f32_e32 v130, v156, v130
	v_add_f32_e32 v130, v157, v130
	v_exp_f32_e32 v195, v131
	v_add_f32_e32 v130, v158, v130
; #define SBAR() __builtin_amdgcn_sched_barrier(0)
; __device__ __forceinline__ void finishSM(f32x16& p0, f32x16& p1, float alpha, float& l_reg, bf16x8& pa0, bf16x8& pa1, bf16x8& pa2, bf16x8& pa3) {
;     ...
;   for (int r = 0; r < 16; ++r) p1[r] = __builtin_amdgcn_exp2f(p1[r]);
;   float ps = 0;
; #pragma unroll
;   for (int r = 0; r < 16; ++r) ps += p0[r];
; #pragma unroll
;   for (int r = 0; r < 16; ++r) ps += p1[r];
;   { auto rr = __builtin_amdgcn_permlane32_swap(__float_as_uint(ps), __float_as_uint(ps), false, false);
;     ps = __uint_as_float(rr[0]) + __uint_as_float(rr[1]); }
;   l_reg = l_reg * alpha + ps;
;     ...
;   PK4(p0, 0, pa0); PK4(p0, 8, pa1); PK4(p1, 0, pa2); PK4(p1, 8, pa3);
; template <int I> __device__ __forceinline__ void pv_step(f32x16* o, int vb, const bf16x8 (&pa)[4], s16x4 (&l)[3], s16x4 (&h)[3]) {
;   if constexpr (I + 2 < 32) pv_rd<(I + 2 < 32 ? I + 2 : 0)>(vb, l[(I + 2) % 3], h[(I + 2) % 3]);
;   if constexpr (I + 2 < 32) asm volatile("s_waitcnt lgkmcnt(4)" ::: "memory"); else if constexpr (I + 1 < 32) asm volatile("s_waitcnt lgkmcnt(2)" ::: "memory"); else asm volatile("s_waitcnt lgkmcnt(0)" ::: "memory");
;   SBAR();
;   const s16x4 L = l[I % 3], H = h[I % 3];
;   o[I >> 2] = __builtin_amdgcn_mfma_f32_32x32x16_bf16(pa[I & 3], (bf16x8){L[0], L[1], L[2], L[3], H[0], H[1], H[2], H[3]}, o[I >> 2], 0, 0, 0);
;   SBAR();
;   if constexpr (I + 1 < 32) pv_step<(I + 1 < 32 ? I + 1 : 31)>(o, vb, pa, l, h);
; }
; __device__ __forceinline__ void pv_all_rolling(f32x16* o, int vb, bf16x8 pa0, bf16x8 pa1, bf16x8 pa2, bf16x8 pa3) {
;   const bf16x8 pa[4] = {pa0, pa1, pa2, pa3}; s16x4 l[3], h[3];
;   asm volatile("s_waitcnt lgkmcnt(0)" ::: "memory");
;   pv_rd<0>(vb, l[0], h[0]); pv_rd<1>(vb, l[1], h[1]);
;   pv_step<0>(o, vb, pa, l, h);
	v_exp_f32_e32 v196, v132
	v_add_f32_e32 v130, v159, v130
	v_exp_f32_e32 v197, v133
	v_add_f32_e32 v130, v160, v130
	v_exp_f32_e32 v198, v134
	v_add_f32_e32 v130, v0, v130
	v_exp_f32_e32 v199, v135
	v_add_f32_e32 v130, v195, v130
	v_exp_f32_e32 v200, v136
	v_add_f32_e32 v130, v196, v130
	v_exp_f32_e32 v201, v137
	v_add_f32_e32 v130, v197, v130
	v_exp_f32_e32 v202, v138
	v_add_f32_e32 v130, v198, v130
	v_exp_f32_e32 v203, v139
	v_add_f32_e32 v130, v199, v130
	v_exp_f32_e32 v204, v140
	v_add_f32_e32 v130, v200, v130
	v_exp_f32_e32 v205, v141
	v_add_f32_e32 v130, v201, v130
	v_exp_f32_e32 v206, v142
	v_add_f32_e32 v130, v202, v130
	v_exp_f32_e32 v207, v143
	v_add_f32_e32 v130, v203, v130
	v_exp_f32_e32 v208, v144
	v_add_f32_e32 v130, v204, v130
	v_exp_f32_e32 v194, v194
	v_add_f32_e32 v130, v205, v130
	v_add_f32_e32 v130, v206, v130
	v_add_f32_e32 v130, v207, v130
	v_add_f32_e32 v130, v208, v130
	v_add_f32_e32 v130, v194, v130
	v_mov_b32_e32 v131, v130
	s_nop 1
	v_permlane32_swap_b32_e32 v130, v131
	v_add_f32_e32 v245, v130, v131
	v_fmac_f32_e32 v245, v161, v222
	v_cvt_pk_bf16_f32 v130, v145, v146
	v_cvt_pk_bf16_f32 v131, v147, v148
	v_cvt_pk_bf16_f32 v132, v149, v150
	v_cvt_pk_bf16_f32 v133, v151, v152
	v_cvt_pk_bf16_f32 v134, v153, v154
	v_cvt_pk_bf16_f32 v135, v155, v156
	v_cvt_pk_bf16_f32 v136, v157, v158
	v_cvt_pk_bf16_f32 v137, v159, v160
	v_cvt_pk_bf16_f32 v138, v0, v195
	v_cvt_pk_bf16_f32 v139, v196, v197
	v_cvt_pk_bf16_f32 v140, v198, v199
	v_cvt_pk_bf16_f32 v141, v200, v201
	v_cvt_pk_bf16_f32 v142, v202, v203
	v_cvt_pk_bf16_f32 v143, v204, v205
	v_cvt_pk_bf16_f32 v144, v206, v207
	v_cvt_pk_bf16_f32 v145, v208, v194
	s_nop 0
	v_permlane32_swap_b32_e32 v130, v132
	v_permlane32_swap_b32_e32 v131, v133
	v_permlane32_swap_b32_e32 v134, v136
	v_permlane32_swap_b32_e32 v135, v137
	v_permlane32_swap_b32_e32 v138, v140
	v_permlane32_swap_b32_e32 v139, v141
	v_permlane32_swap_b32_e32 v142, v144
	v_permlane32_swap_b32_e32 v143, v145
	s_waitcnt vmcnt(0)
	s_barrier
	s_setprio 0
	s_waitcnt lgkmcnt(0)
	ds_read_b64_tr_b16 v[146:147], v244 offset:0
	ds_read_b64_tr_b16 v[148:149], v244 offset:2048
	ds_read_b64_tr_b16 v[150:151], v244 offset:4096
	ds_read_b64_tr_b16 v[152:153], v244 offset:6144
	ds_read_b64_tr_b16 v[154:155], v244 offset:8192
	ds_read_b64_tr_b16 v[156:157], v244 offset:10240
	ds_read_b64_tr_b16 v[158:159], v244 offset:12288
	ds_read_b64_tr_b16 v[160:161], v244 offset:14336
	ds_read_b64_tr_b16 v[194:195], v244 offset:512
	ds_read_b64_tr_b16 v[196:197], v244 offset:2560
	ds_read_b64_tr_b16 v[198:199], v244 offset:4608
	ds_read_b64_tr_b16 v[200:201], v244 offset:6656
	ds_read_b64_tr_b16 v[202:203], v244 offset:8704
	ds_read_b64_tr_b16 v[204:205], v244 offset:10752
	v_lshl_add_u64 v[232:233], v[218:219], 0, s[22:23]
	v_lshl_add_u64 v[232:233], v[232:233], 0, s[14:15]
	s_mov_b32 m0, s29
	s_nop 0
	global_load_lds_dwordx4 v[232:233], off
	s_waitcnt lgkmcnt(12)
	s_nop 0
	v_mfma_f32_32x32x16_bf16 v[114:129], v[130:133], v[146:149], v[114:129]
	ds_read_b64_tr_b16 v[206:207], v244 offset:12800
	ds_read_b64_tr_b16 v[208:209], v244 offset:14848
	v_lshl_add_u64 v[232:233], v[218:219], 0, s[22:23]
	v_lshl_add_u64 v[232:233], v[232:233], 0, s[16:17]
	s_mov_b32 m0, s65
	s_nop 0
	global_load_lds_dwordx4 v[232:233], off
	s_waitcnt lgkmcnt(12)
	v_mfma_f32_32x32x16_bf16 v[114:129], v[134:137], v[150:153], v[114:129]
	ds_read_b64_tr_b16 v[146:147], v244 offset:1024
	ds_read_b64_tr_b16 v[148:149], v244 offset:3072
	v_lshl_add_u64 v[232:233], v[220:221], 0, s[22:23]
	v_lshl_add_u64 v[232:233], v[232:233], 0, s[14:15]
	s_mov_b32 m0, s68
	s_nop 0
	global_load_lds_dwordx4 v[232:233], off
	s_waitcnt lgkmcnt(12)
	v_mfma_f32_32x32x16_bf16 v[114:129], v[138:141], v[154:157], v[114:129]
	ds_read_b64_tr_b16 v[150:151], v244 offset:5120
	ds_read_b64_tr_b16 v[152:153], v244 offset:7168
	v_lshl_add_u64 v[232:233], v[220:221], 0, s[22:23]
	v_lshl_add_u64 v[232:233], v[232:233], 0, s[16:17]
	s_mov_b32 m0, s69
	s_nop 0
	global_load_lds_dwordx4 v[232:233], off
	s_waitcnt lgkmcnt(12)
	v_mfma_f32_32x32x16_bf16 v[114:129], v[142:145], v[158:161], v[114:129]
	ds_read_b64_tr_b16 v[154:155], v244 offset:9216
	ds_read_b64_tr_b16 v[156:157], v244 offset:11264
	s_waitcnt lgkmcnt(12)
	v_mfma_f32_32x32x16_bf16 v[98:113], v[130:133], v[194:197], v[98:113]
	ds_read_b64_tr_b16 v[158:159], v244 offset:13312
	ds_read_b64_tr_b16 v[160:161], v244 offset:15360
	s_waitcnt lgkmcnt(12)
	v_mfma_f32_32x32x16_bf16 v[98:113], v[134:137], v[198:201], v[98:113]
	ds_read_b64_tr_b16 v[194:195], v244 offset:1536
	ds_read_b64_tr_b16 v[196:197], v244 offset:3584
	s_waitcnt lgkmcnt(12)
	v_mfma_f32_32x32x16_bf16 v[98:113], v[138:141], v[202:205], v[98:113]
	ds_read_b64_tr_b16 v[198:199], v244 offset:5632
	ds_read_b64_tr_b16 v[200:201], v244 offset:7680
	s_waitcnt lgkmcnt(12)
	v_mfma_f32_32x32x16_bf16 v[98:113], v[142:145], v[206:209], v[98:113]
	ds_read_b64_tr_b16 v[202:203], v244 offset:9728
	ds_read_b64_tr_b16 v[204:205], v244 offset:11776
	s_waitcnt lgkmcnt(12)
	v_mfma_f32_32x32x16_bf16 v[82:97], v[130:133], v[146:149], v[82:97]
	ds_read_b64_tr_b16 v[206:207], v244 offset:13824
	ds_read_b64_tr_b16 v[208:209], v244 offset:15872
	s_waitcnt lgkmcnt(12)
	v_mfma_f32_32x32x16_bf16 v[82:97], v[134:137], v[150:153], v[82:97]
	ds_read_b64_tr_b16 v[146:147], v244 offset:16384
	ds_read_b64_tr_b16 v[148:149], v244 offset:18432
	s_waitcnt lgkmcnt(12)
	v_mfma_f32_32x32x16_bf16 v[82:97], v[138:141], v[154:157], v[82:97]
	ds_read_b64_tr_b16 v[150:151], v244 offset:20480
	ds_read_b64_tr_b16 v[152:153], v244 offset:22528
	s_waitcnt lgkmcnt(12)
; #define SBAR() __builtin_amdgcn_sched_barrier(0)
; template <int OFF> __device__ __forceinline__ bf16x8 k_read(int a) { bf16x8 r; asm volatile("ds_read_b128 %0, %1 offset:%2" : "=&v"(r) : "v"(a), "i"(OFF) : "memory"); return r; }
; template <int I> __device__ __forceinline__ void pv_step(f32x16* o, int vb, const bf16x8 (&pa)[4], s16x4 (&l)[3], s16x4 (&h)[3]) {
;   if constexpr (I + 2 < 32) pv_rd<(I + 2 < 32 ? I + 2 : 0)>(vb, l[(I + 2) % 3], h[(I + 2) % 3]);
;   if constexpr (I + 2 < 32) asm volatile("s_waitcnt lgkmcnt(4)" ::: "memory"); else if constexpr (I + 1 < 32) asm volatile("s_waitcnt lgkmcnt(2)" ::: "memory"); else asm volatile("s_waitcnt lgkmcnt(0)" ::: "memory");
;   SBAR();
;   const s16x4 L = l[I % 3], H = h[I % 3];
;   o[I >> 2] = __builtin_amdgcn_mfma_f32_32x32x16_bf16(pa[I & 3], (bf16x8){L[0], L[1], L[2], L[3], H[0], H[1], H[2], H[3]}, o[I >> 2], 0, 0, 0);
;   SBAR();
;   if constexpr (I + 1 < 32) pv_step<(I + 1 < 32 ? I + 1 : 31)>(o, vb, pa, l, h);
; }
; __device__ __forceinline__ void pv_all_rolling(f32x16* o, int vb, bf16x8 pa0, bf16x8 pa1, bf16x8 pa2, bf16x8 pa3) {
;   const bf16x8 pa[4] = {pa0, pa1, pa2, pa3}; s16x4 l[3], h[3];
;   asm volatile("s_waitcnt lgkmcnt(0)" ::: "memory");
;   pv_rd<0>(vb, l[0], h[0]); pv_rd<1>(vb, l[1], h[1]);
;   pv_step<0>(o, vb, pa, l, h);
; template <int BUFOFF, int D0> __device__ __forceinline__ void qk_step(f32x16& p0, f32x16& p1, int ka0, const bf16x8 (&qr)[8], bf16x8 (&k0)[2], bf16x8 (&k1)[2]) {
;   if constexpr (D0 + 1 < 8) { const int a_ = ka0 ^ ((D0 + 1) << 5); k0[(D0 + 1) & 1] = k_read<BUFOFF>(a_); k1[(D0 + 1) & 1] = k_read<BUFOFF + 8192>(a_); }
;   if constexpr (D0 + 1 < 8) asm volatile("s_waitcnt lgkmcnt(2)" ::: "memory"); else asm volatile("s_waitcnt lgkmcnt(0)" ::: "memory");
;   SBAR();
;   p0 = __builtin_amdgcn_mfma_f32_32x32x16_bf16(k0[D0 & 1], qr[D0], p0, 0, 0, 0);
;   p1 = __builtin_amdgcn_mfma_f32_32x32x16_bf16(k1[D0 & 1], qr[D0], p1, 0, 0, 0);
;   SBAR();
;   if constexpr (D0 + 1 < 8) qk_step<BUFOFF, (D0 + 1 < 8 ? D0 + 1 : 7)>(p0, p1, ka0, qr, k0, k1);
; }
; template <int BUFOFF> __device__ __forceinline__ void qkt_rolling(f32x16& p0, f32x16& p1, int ka0, const bf16x8 (&qr)[8]) {
;   bf16x8 k0[2], k1[2];
;   asm volatile("s_waitcnt lgkmcnt(0)" ::: "memory");
;   k0[0] = k_read<BUFOFF>(ka0); k1[0] = k_read<BUFOFF + 8192>(ka0);
;   qk_step<BUFOFF, 0>(p0, p1, ka0, qr, k0, k1);
; }
	v_mfma_f32_32x32x16_bf16 v[82:97], v[142:145], v[158:161], v[82:97]
	ds_read_b64_tr_b16 v[154:155], v244 offset:24576
	ds_read_b64_tr_b16 v[156:157], v244 offset:26624
	s_waitcnt lgkmcnt(12)
	v_mfma_f32_32x32x16_bf16 v[66:81], v[130:133], v[194:197], v[66:81]
	ds_read_b64_tr_b16 v[158:159], v244 offset:28672
	ds_read_b64_tr_b16 v[160:161], v244 offset:30720
	s_waitcnt lgkmcnt(12)
	v_mfma_f32_32x32x16_bf16 v[66:81], v[134:137], v[198:201], v[66:81]
	ds_read_b64_tr_b16 v[194:195], v244 offset:16896
	ds_read_b64_tr_b16 v[196:197], v244 offset:18944
	s_waitcnt lgkmcnt(12)
	v_mfma_f32_32x32x16_bf16 v[66:81], v[138:141], v[202:205], v[66:81]
	ds_read_b64_tr_b16 v[198:199], v244 offset:20992
	ds_read_b64_tr_b16 v[200:201], v244 offset:23040
	s_waitcnt lgkmcnt(12)
	v_mfma_f32_32x32x16_bf16 v[66:81], v[142:145], v[206:209], v[66:81]
	ds_read_b64_tr_b16 v[202:203], v244 offset:25088
	ds_read_b64_tr_b16 v[204:205], v244 offset:27136
	s_waitcnt lgkmcnt(12)
	v_mfma_f32_32x32x16_bf16 v[50:65], v[130:133], v[146:149], v[50:65]
	ds_read_b64_tr_b16 v[206:207], v244 offset:29184
	ds_read_b64_tr_b16 v[208:209], v244 offset:31232
	s_waitcnt lgkmcnt(12)
	v_mfma_f32_32x32x16_bf16 v[50:65], v[134:137], v[150:153], v[50:65]
	ds_read_b64_tr_b16 v[146:147], v244 offset:17408
	ds_read_b64_tr_b16 v[148:149], v244 offset:19456
	s_waitcnt lgkmcnt(12)
	v_mfma_f32_32x32x16_bf16 v[50:65], v[138:141], v[154:157], v[50:65]
	ds_read_b64_tr_b16 v[150:151], v244 offset:21504
	ds_read_b64_tr_b16 v[152:153], v244 offset:23552
	s_waitcnt lgkmcnt(12)
	v_mfma_f32_32x32x16_bf16 v[50:65], v[142:145], v[158:161], v[50:65]
	ds_read_b64_tr_b16 v[154:155], v244 offset:25600
	ds_read_b64_tr_b16 v[156:157], v244 offset:27648
	s_waitcnt lgkmcnt(12)
	v_mfma_f32_32x32x16_bf16 v[34:49], v[130:133], v[194:197], v[34:49]
	ds_read_b64_tr_b16 v[158:159], v244 offset:29696
	ds_read_b64_tr_b16 v[160:161], v244 offset:31744
	s_waitcnt lgkmcnt(12)
	v_mfma_f32_32x32x16_bf16 v[34:49], v[134:137], v[198:201], v[34:49]
	ds_read_b64_tr_b16 v[194:195], v244 offset:17920
	ds_read_b64_tr_b16 v[196:197], v244 offset:19968
	s_waitcnt lgkmcnt(12)
	v_mfma_f32_32x32x16_bf16 v[34:49], v[138:141], v[202:205], v[34:49]
	ds_read_b64_tr_b16 v[198:199], v244 offset:22016
	ds_read_b64_tr_b16 v[200:201], v244 offset:24064
	s_waitcnt lgkmcnt(12)
	v_mfma_f32_32x32x16_bf16 v[34:49], v[142:145], v[206:209], v[34:49]
	ds_read_b64_tr_b16 v[202:203], v244 offset:26112
	ds_read_b64_tr_b16 v[204:205], v244 offset:28160
	s_waitcnt lgkmcnt(12)
	v_mfma_f32_32x32x16_bf16 v[18:33], v[130:133], v[146:149], v[18:33]
	ds_read_b64_tr_b16 v[206:207], v244 offset:30208
	ds_read_b64_tr_b16 v[208:209], v244 offset:32256
	s_waitcnt lgkmcnt(12)
	v_mfma_f32_32x32x16_bf16 v[18:33], v[134:137], v[150:153], v[18:33]
	s_waitcnt lgkmcnt(10)
	v_mfma_f32_32x32x16_bf16 v[18:33], v[138:141], v[154:157], v[18:33]
	s_waitcnt lgkmcnt(8)
	v_mfma_f32_32x32x16_bf16 v[18:33], v[142:145], v[158:161], v[18:33]
	s_waitcnt lgkmcnt(6)
	v_mfma_f32_32x32x16_bf16 v[2:17], v[130:133], v[194:197], v[2:17]
	s_waitcnt lgkmcnt(4)
	v_mfma_f32_32x32x16_bf16 v[2:17], v[134:137], v[198:201], v[2:17]
	s_waitcnt lgkmcnt(2)
	v_mfma_f32_32x32x16_bf16 v[2:17], v[138:141], v[202:205], v[2:17]
	s_waitcnt lgkmcnt(0)
	v_mfma_f32_32x32x16_bf16 v[2:17], v[142:145], v[206:209], v[2:17]
	s_waitcnt vmcnt(0)
	s_add_u32 s22, s22, 0x180000
	s_addc_u32 s23, s23, 0
	s_add_i32 s80, s80, 2
	s_and_b64 vcc, exec, s[46:47]
	s_waitcnt vmcnt(0) lgkmcnt(0)
	s_barrier
	s_cbranch_vccnz .LBB0_439
.LBB0_430:
	s_setprio 1
	v_lshl_add_u64 v[224:225], v[214:215], 0, s[22:23]
	v_lshl_add_u64 v[228:229], v[216:217], 0, s[22:23]
	s_waitcnt lgkmcnt(0)
	ds_read_b128 v[194:197], v235 offset:0
	ds_read_b128 v[198:201], v236 offset:0
	ds_read_b128 v[202:205], v238 offset:0
	ds_read_b128 v[206:209], v239 offset:0
	ds_read_b128 v[130:133], v240 offset:0
	ds_read_b128 v[134:137], v241 offset:0
	ds_read_b128 v[138:141], v242 offset:0
	ds_read_b128 v[142:145], v243 offset:0
	v_lshl_add_u64 v[232:233], v[224:225], 0, s[10:11]
	s_add_i32 m0, s62, s25
	s_nop 0
	global_load_lds_dwordx4 v[232:233], off
	v_lshl_add_u64 v[232:233], v[228:229], 0, s[10:11]
	s_add_i32 m0, s62, s66
	s_nop 0
	global_load_lds_dwordx4 v[232:233], off
	s_waitcnt lgkmcnt(7)
	s_nop 0
	v_mfma_f32_32x32x16_bf16 v[146:161], v[194:197], v[162:165], 0
	ds_read_b128 v[194:197], v235 offset:8192
	s_waitcnt lgkmcnt(7)
	v_mfma_f32_32x32x16_bf16 v[146:161], v[198:201], v[166:169], v[146:161]
	ds_read_b128 v[198:201], v236 offset:8192
	s_waitcnt lgkmcnt(7)
	v_mfma_f32_32x32x16_bf16 v[146:161], v[202:205], v[170:173], v[146:161]
	ds_read_b128 v[202:205], v238 offset:8192
	s_waitcnt lgkmcnt(7)
	v_mfma_f32_32x32x16_bf16 v[146:161], v[206:209], v[174:177], v[146:161]
	ds_read_b128 v[206:209], v239 offset:8192
	s_waitcnt lgkmcnt(7)
	v_mfma_f32_32x32x16_bf16 v[146:161], v[130:133], v[178:181], v[146:161]
	s_waitcnt lgkmcnt(6)
	v_mfma_f32_32x32x16_bf16 v[146:161], v[134:137], v[182:185], v[146:161]
	s_waitcnt lgkmcnt(5)
	v_mfma_f32_32x32x16_bf16 v[146:161], v[138:141], v[186:189], v[146:161]
	s_waitcnt lgkmcnt(4)
	v_mfma_f32_32x32x16_bf16 v[146:161], v[142:145], v[190:193], v[146:161]
	s_waitcnt lgkmcnt(3)
	v_mfma_f32_32x32x16_bf16 v[130:145], v[194:197], v[162:165], 0
	ds_read_b128 v[194:197], v240 offset:8192
	s_waitcnt lgkmcnt(3)
	v_mfma_f32_32x32x16_bf16 v[130:145], v[198:201], v[166:169], v[130:145]
	ds_read_b128 v[198:201], v241 offset:8192
	s_waitcnt lgkmcnt(3)
	v_mfma_f32_32x32x16_bf16 v[130:145], v[202:205], v[170:173], v[130:145]
	ds_read_b128 v[202:205], v242 offset:8192
	s_waitcnt lgkmcnt(3)
; #define SBAR() __builtin_amdgcn_sched_barrier(0)
; template <int OFF> __device__ __forceinline__ bf16x8 k_read(int a) { bf16x8 r; asm volatile("ds_read_b128 %0, %1 offset:%2" : "=&v"(r) : "v"(a), "i"(OFF) : "memory"); return r; }
; __device__ __forceinline__ void partialSM(f32x16& p0, f32x16& p1, float& m_reg, float& mn, float& alpha) {
;   constexpr float C = SCALE * 1.4426950408889634f;
;   float pmax = p0[0];
; #pragma unroll
;   for (int r = 1; r < 16; ++r) pmax = fmaxf(pmax, p0[r]);
; #pragma unroll
;   for (int r = 0; r < 16; ++r) pmax = fmaxf(pmax, p1[r]);
;   { auto rr = __builtin_amdgcn_permlane32_swap(__float_as_uint(pmax), __float_as_uint(pmax), false, false);
;     pmax = fmaxf(__uint_as_float(rr[0]), __uint_as_float(rr[1])); }
;   if (__builtin_expect(__all(pmax - m_reg <= THR / SCALE), 1)) { mn = m_reg; alpha = 1.f; }
;   else { mn = fmaxf(m_reg, pmax); alpha = __builtin_amdgcn_exp2f((m_reg - mn) * C); m_reg = mn; }
; template <int BUFOFF, int D0> __device__ __forceinline__ void qk_step(f32x16& p0, f32x16& p1, int ka0, const bf16x8 (&qr)[8], bf16x8 (&k0)[2], bf16x8 (&k1)[2]) {
;   if constexpr (D0 + 1 < 8) { const int a_ = ka0 ^ ((D0 + 1) << 5); k0[(D0 + 1) & 1] = k_read<BUFOFF>(a_); k1[(D0 + 1) & 1] = k_read<BUFOFF + 8192>(a_); }
;   if constexpr (D0 + 1 < 8) asm volatile("s_waitcnt lgkmcnt(2)" ::: "memory"); else asm volatile("s_waitcnt lgkmcnt(0)" ::: "memory");
;   SBAR();
;   p0 = __builtin_amdgcn_mfma_f32_32x32x16_bf16(k0[D0 & 1], qr[D0], p0, 0, 0, 0);
;   p1 = __builtin_amdgcn_mfma_f32_32x32x16_bf16(k1[D0 & 1], qr[D0], p1, 0, 0, 0);
;   SBAR();
;   if constexpr (D0 + 1 < 8) qk_step<BUFOFF, (D0 + 1 < 8 ? D0 + 1 : 7)>(p0, p1, ka0, qr, k0, k1);
; }
; template <int BUFOFF> __device__ __forceinline__ void qkt_rolling(f32x16& p0, f32x16& p1, int ka0, const bf16x8 (&qr)[8]) {
;   bf16x8 k0[2], k1[2];
;   asm volatile("s_waitcnt lgkmcnt(0)" ::: "memory");
;   k0[0] = k_read<BUFOFF>(ka0); k1[0] = k_read<BUFOFF + 8192>(ka0);
;   qk_step<BUFOFF, 0>(p0, p1, ka0, qr, k0, k1);
; }
	v_mfma_f32_32x32x16_bf16 v[130:145], v[206:209], v[174:177], v[130:145]
	ds_read_b128 v[206:209], v243 offset:8192
	s_waitcnt lgkmcnt(3)
	v_mfma_f32_32x32x16_bf16 v[130:145], v[194:197], v[178:181], v[130:145]
	s_waitcnt lgkmcnt(2)
	v_mfma_f32_32x32x16_bf16 v[130:145], v[198:201], v[182:185], v[130:145]
	s_waitcnt lgkmcnt(1)
	v_mfma_f32_32x32x16_bf16 v[130:145], v[202:205], v[186:189], v[130:145]
	s_waitcnt lgkmcnt(0)
	v_mfma_f32_32x32x16_bf16 v[130:145], v[206:209], v[190:193], v[130:145]
	s_nop 10
	v_max_f32_e32 v0, v147, v147
	v_max_f32_e32 v194, v146, v146
	v_max_f32_e32 v0, v194, v0
	v_max3_f32 v0, v0, v148, v149
	v_max3_f32 v0, v0, v150, v151
	v_max3_f32 v0, v0, v152, v153
	v_max3_f32 v0, v0, v154, v155
	v_max3_f32 v0, v0, v156, v157
	v_max3_f32 v0, v0, v158, v159
	v_max3_f32 v0, v0, v160, v161
	v_max3_f32 v0, v0, v130, v131
	v_max3_f32 v0, v0, v132, v133
	v_max3_f32 v0, v0, v134, v135
	v_max3_f32 v0, v0, v136, v137
	v_max3_f32 v0, v0, v138, v139
	v_max3_f32 v0, v0, v140, v141
	v_max3_f32 v0, v0, v142, v143
	v_max3_f32 v0, v0, v144, v145
	v_mov_b32_e32 v194, v0
	s_nop 1
	v_permlane32_swap_b32_e32 v0, v194
	v_max_f32_e32 v194, v194, v194
	v_max_f32_e32 v0, v0, v0
	v_max_f32_e32 v0, v0, v194
	v_sub_f32_e32 v194, v0, v246
	v_cmp_ge_f32_e32 vcc, s63, v194
	v_max_f32_e32 v194, v246, v246
	v_max_f32_e32 v247, v194, v0
	v_sub_f32_e32 v0, v246, v247
	v_mul_f32_e32 v0, 0x3e0293ee, v0
	v_exp_f32_e32 v0, v0
	s_cmp_eq_u64 vcc, exec
	s_cselect_b64 s[6:7], -1, 0
	v_cndmask_b32_e64 v0, v0, 1.0, s[6:7]
	v_cmp_gt_f32_e32 vcc, 1.0, v0
	s_cbranch_vccz .LBB0_434
	s_and_saveexec_b64 s[46:47], s[4:5]
	ds_write_b32 v237, v0 offset:128
	s_or_b64 exec, exec, s[46:47]
	s_waitcnt lgkmcnt(0)
	v_add_u32_e32 v194, s24, v212
	ds_read_b128 v[206:209], v194 offset:224
	ds_read_b128 v[202:205], v194 offset:192
	ds_read_b128 v[198:201], v194 offset:160
	ds_read_b128 v[194:197], v194 offset:128
	s_waitcnt lgkmcnt(0)
	v_pk_mul_f32 v[126:127], v[126:127], v[206:207]
	v_pk_mul_f32 v[122:123], v[122:123], v[202:203]
	v_pk_mul_f32 v[118:119], v[118:119], v[198:199]
	v_pk_mul_f32 v[128:129], v[128:129], v[208:209]
	v_pk_mul_f32 v[124:125], v[124:125], v[204:205]
	v_pk_mul_f32 v[120:121], v[120:121], v[200:201]
	v_pk_mul_f32 v[116:117], v[116:117], v[196:197]
	v_pk_mul_f32 v[114:115], v[114:115], v[194:195]
	v_pk_mul_f32 v[110:111], v[110:111], v[206:207]
	v_pk_mul_f32 v[106:107], v[106:107], v[202:203]
	v_pk_mul_f32 v[102:103], v[102:103], v[198:199]
	v_pk_mul_f32 v[112:113], v[112:113], v[208:209]
	v_pk_mul_f32 v[108:109], v[108:109], v[204:205]
	v_pk_mul_f32 v[104:105], v[104:105], v[200:201]
	v_pk_mul_f32 v[100:101], v[100:101], v[196:197]
	v_pk_mul_f32 v[98:99], v[98:99], v[194:195]
	v_pk_mul_f32 v[94:95], v[94:95], v[206:207]
	v_pk_mul_f32 v[90:91], v[90:91], v[202:203]
	v_pk_mul_f32 v[86:87], v[86:87], v[198:199]
	v_pk_mul_f32 v[96:97], v[96:97], v[208:209]
	v_pk_mul_f32 v[92:93], v[92:93], v[204:205]
	v_pk_mul_f32 v[88:89], v[88:89], v[200:201]
	v_pk_mul_f32 v[84:85], v[84:85], v[196:197]
	v_pk_mul_f32 v[82:83], v[82:83], v[194:195]
	v_pk_mul_f32 v[78:79], v[78:79], v[206:207]
	v_pk_mul_f32 v[74:75], v[74:75], v[202:203]
	v_pk_mul_f32 v[70:71], v[70:71], v[198:199]
	v_pk_mul_f32 v[80:81], v[80:81], v[208:209]
	v_pk_mul_f32 v[76:77], v[76:77], v[204:205]
	v_pk_mul_f32 v[72:73], v[72:73], v[200:201]
	v_pk_mul_f32 v[68:69], v[68:69], v[196:197]
	v_pk_mul_f32 v[66:67], v[66:67], v[194:195]
	v_pk_mul_f32 v[62:63], v[62:63], v[206:207]
	v_pk_mul_f32 v[58:59], v[58:59], v[202:203]
	v_pk_mul_f32 v[54:55], v[54:55], v[198:199]
	v_pk_mul_f32 v[64:65], v[64:65], v[208:209]
	v_pk_mul_f32 v[60:61], v[60:61], v[204:205]
	v_pk_mul_f32 v[56:57], v[56:57], v[200:201]
	v_pk_mul_f32 v[52:53], v[52:53], v[196:197]
	v_pk_mul_f32 v[50:51], v[50:51], v[194:195]
	v_pk_mul_f32 v[46:47], v[46:47], v[206:207]
	v_pk_mul_f32 v[42:43], v[42:43], v[202:203]
	v_pk_mul_f32 v[38:39], v[38:39], v[198:199]
	v_pk_mul_f32 v[48:49], v[48:49], v[208:209]
	v_pk_mul_f32 v[44:45], v[44:45], v[204:205]
	v_pk_mul_f32 v[40:41], v[40:41], v[200:201]
	v_pk_mul_f32 v[36:37], v[36:37], v[196:197]
	v_pk_mul_f32 v[34:35], v[34:35], v[194:195]
	v_pk_mul_f32 v[30:31], v[30:31], v[206:207]
	v_pk_mul_f32 v[26:27], v[26:27], v[202:203]
	v_pk_mul_f32 v[22:23], v[22:23], v[198:199]
	v_pk_mul_f32 v[32:33], v[32:33], v[208:209]
	v_pk_mul_f32 v[28:29], v[28:29], v[204:205]
	v_pk_mul_f32 v[24:25], v[24:25], v[200:201]
	v_pk_mul_f32 v[20:21], v[20:21], v[196:197]
	v_pk_mul_f32 v[18:19], v[18:19], v[194:195]
	v_pk_mul_f32 v[14:15], v[14:15], v[206:207]
	v_pk_mul_f32 v[10:11], v[10:11], v[202:203]
	v_pk_mul_f32 v[6:7], v[6:7], v[198:199]
	v_pk_mul_f32 v[16:17], v[16:17], v[208:209]
	v_pk_mul_f32 v[12:13], v[12:13], v[204:205]
	v_pk_mul_f32 v[8:9], v[8:9], v[200:201]
	v_pk_mul_f32 v[4:5], v[4:5], v[196:197]
	v_pk_mul_f32 v[2:3], v[2:3], v[194:195]
; __device__ __forceinline__ void partialSM(f32x16& p0, f32x16& p1, float& m_reg, float& mn, float& alpha) {
;     ...
;   float mnC = -mn * C;
; #pragma unroll
;   for (int r = 0; r < 16; ++r) p0[r] = fmaf(p0[r], C, mnC);
; #pragma unroll
;   for (int r = 0; r < 16; ++r) p1[r] = fmaf(p1[r], C, mnC);
; #pragma unroll
;   for (int r = 0; r < 16; ++r) p0[r] = __builtin_amdgcn_exp2f(p0[r]);
; }
; __device__ __forceinline__ void finishSM(f32x16& p0, f32x16& p1, float alpha, float& l_reg, bf16x8& pa0, bf16x8& pa1, bf16x8& pa2, bf16x8& pa3) {
; #pragma unroll
;   for (int r = 0; r < 16; ++r) p1[r] = __builtin_amdgcn_exp2f(p1[r]);
;   float ps = 0;
; #pragma unroll
;   for (int r = 0; r < 16; ++r) ps += p0[r];
; #pragma unroll
;   for (int r = 0; r < 16; ++r) ps += p1[r];
;   { auto rr = __builtin_amdgcn_permlane32_swap(__float_as_uint(ps), __float_as_uint(ps), false, false);
;     ps = __uint_as_float(rr[0]) + __uint_as_float(rr[1]); }
;   l_reg = l_reg * alpha + ps;
;     ...
;   PK4(p0, 0, pa0); PK4(p0, 8, pa1); PK4(p1, 0, pa2); PK4(p1, 8, pa3);
.LBB0_434:
	v_cndmask_b32_e64 v246, v247, v246, s[6:7]
	v_mul_f32_e32 v194, 0xbe0293ee, v246
	v_fmamk_f32 v146, v146, 0x3e0293ee, v194
	v_fmamk_f32 v147, v147, 0x3e0293ee, v194
	v_fmamk_f32 v148, v148, 0x3e0293ee, v194
	v_fmamk_f32 v149, v149, 0x3e0293ee, v194
	v_fmamk_f32 v150, v150, 0x3e0293ee, v194
	v_fmamk_f32 v151, v151, 0x3e0293ee, v194
	v_fmamk_f32 v152, v152, 0x3e0293ee, v194
	v_fmamk_f32 v153, v153, 0x3e0293ee, v194
	v_fmamk_f32 v154, v154, 0x3e0293ee, v194
	v_fmamk_f32 v155, v155, 0x3e0293ee, v194
	v_fmamk_f32 v156, v156, 0x3e0293ee, v194
	v_fmamk_f32 v157, v157, 0x3e0293ee, v194
	v_fmamk_f32 v158, v158, 0x3e0293ee, v194
	v_fmamk_f32 v159, v159, 0x3e0293ee, v194
	v_fmamk_f32 v160, v160, 0x3e0293ee, v194
	v_fmamk_f32 v161, v161, 0x3e0293ee, v194
	v_fmamk_f32 v130, v130, 0x3e0293ee, v194
	v_fmamk_f32 v131, v131, 0x3e0293ee, v194
	v_fmamk_f32 v132, v132, 0x3e0293ee, v194
	v_fmamk_f32 v133, v133, 0x3e0293ee, v194
	v_fmamk_f32 v134, v134, 0x3e0293ee, v194
	v_fmamk_f32 v135, v135, 0x3e0293ee, v194
	v_fmamk_f32 v136, v136, 0x3e0293ee, v194
	v_fmamk_f32 v137, v137, 0x3e0293ee, v194
	v_fmamk_f32 v138, v138, 0x3e0293ee, v194
	v_fmamk_f32 v139, v139, 0x3e0293ee, v194
	v_fmamk_f32 v140, v140, 0x3e0293ee, v194
	v_fmamk_f32 v141, v141, 0x3e0293ee, v194
	v_fmamk_f32 v142, v142, 0x3e0293ee, v194
	v_fmamk_f32 v143, v143, 0x3e0293ee, v194
	v_fmamk_f32 v144, v144, 0x3e0293ee, v194
	v_fmac_f32_e32 v194, 0x3e0293ee, v145
	v_exp_f32_e32 v145, v146
	v_exp_f32_e32 v146, v147
	v_exp_f32_e32 v147, v148
	v_exp_f32_e32 v148, v149
	v_exp_f32_e32 v149, v150
	v_exp_f32_e32 v150, v151
	v_exp_f32_e32 v151, v152
	v_exp_f32_e32 v152, v153
	v_exp_f32_e32 v153, v154
	v_exp_f32_e32 v154, v155
	v_exp_f32_e32 v155, v156
	v_exp_f32_e32 v156, v157
	v_exp_f32_e32 v157, v158
	v_exp_f32_e32 v158, v159
	v_exp_f32_e32 v159, v160
	v_exp_f32_e32 v160, v161
	v_exp_f32_e32 v161, v130
	v_add_f32_e32 v130, 0, v145
	v_add_f32_e32 v130, v146, v130
	v_add_f32_e32 v130, v147, v130
	v_add_f32_e32 v130, v148, v130
	v_add_f32_e32 v130, v149, v130
	v_add_f32_e32 v130, v150, v130
	v_add_f32_e32 v130, v151, v130
	v_add_f32_e32 v130, v152, v130
	v_add_f32_e32 v130, v153, v130
	v_add_f32_e32 v130, v154, v130
	v_add_f32_e32 v130, v155, v130
	v_add_f32_e32 v130, v156, v130
	v_add_f32_e32 v130, v157, v130
	v_exp_f32_e32 v195, v131
	v_add_f32_e32 v130, v158, v130
	v_exp_f32_e32 v196, v132
	v_add_f32_e32 v130, v159, v130
	v_exp_f32_e32 v197, v133
	v_add_f32_e32 v130, v160, v130
	v_exp_f32_e32 v198, v134
	v_add_f32_e32 v130, v161, v130
	v_exp_f32_e32 v199, v135
	v_add_f32_e32 v130, v195, v130
	v_exp_f32_e32 v200, v136
	v_add_f32_e32 v130, v196, v130
	v_exp_f32_e32 v201, v137
	v_add_f32_e32 v130, v197, v130
	v_exp_f32_e32 v202, v138
	v_add_f32_e32 v130, v198, v130
	v_exp_f32_e32 v203, v139
	v_add_f32_e32 v130, v199, v130
	v_exp_f32_e32 v204, v140
	v_add_f32_e32 v130, v200, v130
	v_exp_f32_e32 v205, v141
	v_add_f32_e32 v130, v201, v130
	v_exp_f32_e32 v206, v142
	v_add_f32_e32 v130, v202, v130
	v_exp_f32_e32 v207, v143
	v_add_f32_e32 v130, v203, v130
	v_exp_f32_e32 v208, v144
	v_add_f32_e32 v130, v204, v130
	v_exp_f32_e32 v194, v194
	v_add_f32_e32 v130, v205, v130
	v_add_f32_e32 v130, v206, v130
	v_add_f32_e32 v130, v207, v130
	v_add_f32_e32 v130, v208, v130
	v_add_f32_e32 v247, v194, v130
	v_mov_b32_e32 v248, v247
	s_nop 1
	v_permlane32_swap_b32_e32 v247, v248
	v_cvt_pk_bf16_f32 v130, v145, v146
	v_cvt_pk_bf16_f32 v131, v147, v148
	v_cvt_pk_bf16_f32 v132, v149, v150
	v_cvt_pk_bf16_f32 v133, v151, v152
	v_cvt_pk_bf16_f32 v134, v153, v154
	v_cvt_pk_bf16_f32 v135, v155, v156
	v_cvt_pk_bf16_f32 v136, v157, v158
	v_cvt_pk_bf16_f32 v137, v159, v160
	v_cvt_pk_bf16_f32 v138, v161, v195
	v_cvt_pk_bf16_f32 v139, v196, v197
	v_cvt_pk_bf16_f32 v140, v198, v199
	v_cvt_pk_bf16_f32 v141, v200, v201
	v_cvt_pk_bf16_f32 v142, v202, v203
	v_cvt_pk_bf16_f32 v143, v204, v205
	v_cvt_pk_bf16_f32 v144, v206, v207
	v_cvt_pk_bf16_f32 v145, v208, v194
	s_nop 0
	v_permlane32_swap_b32_e32 v130, v132
	v_permlane32_swap_b32_e32 v131, v133
	v_permlane32_swap_b32_e32 v134, v136
	v_permlane32_swap_b32_e32 v135, v137
	v_permlane32_swap_b32_e32 v138, v140
	v_permlane32_swap_b32_e32 v139, v141
	v_permlane32_swap_b32_e32 v142, v144
	v_permlane32_swap_b32_e32 v143, v145
	s_waitcnt vmcnt(0)
	s_barrier
; #define SBAR() __builtin_amdgcn_sched_barrier(0)
; template <int I> __device__ __forceinline__ void pv_step(f32x16* o, int vb, const bf16x8 (&pa)[4], s16x4 (&l)[3], s16x4 (&h)[3]) {
;   if constexpr (I + 2 < 32) pv_rd<(I + 2 < 32 ? I + 2 : 0)>(vb, l[(I + 2) % 3], h[(I + 2) % 3]);
;   if constexpr (I + 2 < 32) asm volatile("s_waitcnt lgkmcnt(4)" ::: "memory"); else if constexpr (I + 1 < 32) asm volatile("s_waitcnt lgkmcnt(2)" ::: "memory"); else asm volatile("s_waitcnt lgkmcnt(0)" ::: "memory");
;   SBAR();
;   const s16x4 L = l[I % 3], H = h[I % 3];
;   o[I >> 2] = __builtin_amdgcn_mfma_f32_32x32x16_bf16(pa[I & 3], (bf16x8){L[0], L[1], L[2], L[3], H[0], H[1], H[2], H[3]}, o[I >> 2], 0, 0, 0);
;   SBAR();
;   if constexpr (I + 1 < 32) pv_step<(I + 1 < 32 ? I + 1 : 31)>(o, vb, pa, l, h);
; }
; __device__ __forceinline__ void pv_all_rolling(f32x16* o, int vb, bf16x8 pa0, bf16x8 pa1, bf16x8 pa2, bf16x8 pa3) {
;   const bf16x8 pa[4] = {pa0, pa1, pa2, pa3}; s16x4 l[3], h[3];
;   asm volatile("s_waitcnt lgkmcnt(0)" ::: "memory");
;   pv_rd<0>(vb, l[0], h[0]); pv_rd<1>(vb, l[1], h[1]);
;   pv_step<0>(o, vb, pa, l, h);
	s_setprio 0
	s_waitcnt lgkmcnt(0)
	ds_read_b64_tr_b16 v[146:147], v213 offset:0
	ds_read_b64_tr_b16 v[148:149], v213 offset:2048
	ds_read_b64_tr_b16 v[150:151], v213 offset:4096
	ds_read_b64_tr_b16 v[152:153], v213 offset:6144
	ds_read_b64_tr_b16 v[154:155], v213 offset:8192
	ds_read_b64_tr_b16 v[156:157], v213 offset:10240
	ds_read_b64_tr_b16 v[158:159], v213 offset:12288
	ds_read_b64_tr_b16 v[160:161], v213 offset:14336
	ds_read_b64_tr_b16 v[194:195], v213 offset:512
	ds_read_b64_tr_b16 v[196:197], v213 offset:2560
	ds_read_b64_tr_b16 v[198:199], v213 offset:4608
	ds_read_b64_tr_b16 v[200:201], v213 offset:6656
	ds_read_b64_tr_b16 v[202:203], v213 offset:8704
	ds_read_b64_tr_b16 v[204:205], v213 offset:10752
	v_lshl_add_u64 v[232:233], v[218:219], 0, s[22:23]
	v_lshl_add_u64 v[232:233], v[232:233], 0, s[10:11]
	s_add_i32 m0, s29, 0x8000
	s_nop 0
	global_load_lds_dwordx4 v[232:233], off
	s_waitcnt lgkmcnt(12)
	s_nop 0
	v_mfma_f32_32x32x16_bf16 v[114:129], v[130:133], v[146:149], v[114:129]
	ds_read_b64_tr_b16 v[206:207], v213 offset:12800
	ds_read_b64_tr_b16 v[208:209], v213 offset:14848
	v_lshl_add_u64 v[232:233], v[218:219], 0, s[22:23]
	v_lshl_add_u64 v[232:233], v[232:233], 0, s[12:13]
	s_add_i32 m0, s29, 0xc000
	s_nop 0
	global_load_lds_dwordx4 v[232:233], off
	s_waitcnt lgkmcnt(12)
	v_mfma_f32_32x32x16_bf16 v[114:129], v[134:137], v[150:153], v[114:129]
	ds_read_b64_tr_b16 v[146:147], v213 offset:1024
	ds_read_b64_tr_b16 v[148:149], v213 offset:3072
	v_lshl_add_u64 v[232:233], v[220:221], 0, s[22:23]
	v_lshl_add_u64 v[232:233], v[232:233], 0, s[10:11]
	s_add_i32 m0, s29, 0x8400
	s_nop 0
	global_load_lds_dwordx4 v[232:233], off
	s_waitcnt lgkmcnt(12)
	v_mfma_f32_32x32x16_bf16 v[114:129], v[138:141], v[154:157], v[114:129]
	ds_read_b64_tr_b16 v[150:151], v213 offset:5120
	ds_read_b64_tr_b16 v[152:153], v213 offset:7168
	v_lshl_add_u64 v[232:233], v[220:221], 0, s[22:23]
	v_lshl_add_u64 v[232:233], v[232:233], 0, s[12:13]
	s_add_i32 m0, s29, 0xc400
	s_nop 0
	global_load_lds_dwordx4 v[232:233], off
	s_waitcnt lgkmcnt(12)
	v_mfma_f32_32x32x16_bf16 v[114:129], v[142:145], v[158:161], v[114:129]
	ds_read_b64_tr_b16 v[154:155], v213 offset:9216
	ds_read_b64_tr_b16 v[156:157], v213 offset:11264
	s_waitcnt lgkmcnt(12)
	v_mfma_f32_32x32x16_bf16 v[98:113], v[130:133], v[194:197], v[98:113]
	ds_read_b64_tr_b16 v[158:159], v213 offset:13312
	ds_read_b64_tr_b16 v[160:161], v213 offset:15360
	s_waitcnt lgkmcnt(12)
	v_mfma_f32_32x32x16_bf16 v[98:113], v[134:137], v[198:201], v[98:113]
	ds_read_b64_tr_b16 v[194:195], v213 offset:1536
	ds_read_b64_tr_b16 v[196:197], v213 offset:3584
	s_waitcnt lgkmcnt(12)
	v_mfma_f32_32x32x16_bf16 v[98:113], v[138:141], v[202:205], v[98:113]
	ds_read_b64_tr_b16 v[198:199], v213 offset:5632
	ds_read_b64_tr_b16 v[200:201], v213 offset:7680
	s_waitcnt lgkmcnt(12)
	v_mfma_f32_32x32x16_bf16 v[98:113], v[142:145], v[206:209], v[98:113]
	ds_read_b64_tr_b16 v[202:203], v213 offset:9728
	ds_read_b64_tr_b16 v[204:205], v213 offset:11776
	s_waitcnt lgkmcnt(12)
	v_mfma_f32_32x32x16_bf16 v[82:97], v[130:133], v[146:149], v[82:97]
	ds_read_b64_tr_b16 v[206:207], v213 offset:13824
	ds_read_b64_tr_b16 v[208:209], v213 offset:15872
	s_waitcnt lgkmcnt(12)
	v_mfma_f32_32x32x16_bf16 v[82:97], v[134:137], v[150:153], v[82:97]
	ds_read_b64_tr_b16 v[146:147], v213 offset:16384
	ds_read_b64_tr_b16 v[148:149], v213 offset:18432
	s_waitcnt lgkmcnt(12)
	v_mfma_f32_32x32x16_bf16 v[82:97], v[138:141], v[154:157], v[82:97]
	ds_read_b64_tr_b16 v[150:151], v213 offset:20480
	ds_read_b64_tr_b16 v[152:153], v213 offset:22528
	s_waitcnt lgkmcnt(12)
	v_mfma_f32_32x32x16_bf16 v[82:97], v[142:145], v[158:161], v[82:97]
	ds_read_b64_tr_b16 v[154:155], v213 offset:24576
	ds_read_b64_tr_b16 v[156:157], v213 offset:26624
	s_waitcnt lgkmcnt(12)
	v_mfma_f32_32x32x16_bf16 v[66:81], v[130:133], v[194:197], v[66:81]
	ds_read_b64_tr_b16 v[158:159], v213 offset:28672
	ds_read_b64_tr_b16 v[160:161], v213 offset:30720
	s_waitcnt lgkmcnt(12)
	v_mfma_f32_32x32x16_bf16 v[66:81], v[134:137], v[198:201], v[66:81]
	ds_read_b64_tr_b16 v[194:195], v213 offset:16896
	ds_read_b64_tr_b16 v[196:197], v213 offset:18944
	s_waitcnt lgkmcnt(12)
	v_mfma_f32_32x32x16_bf16 v[66:81], v[138:141], v[202:205], v[66:81]
	ds_read_b64_tr_b16 v[198:199], v213 offset:20992
	ds_read_b64_tr_b16 v[200:201], v213 offset:23040
	s_waitcnt lgkmcnt(12)
	v_mfma_f32_32x32x16_bf16 v[66:81], v[142:145], v[206:209], v[66:81]
	ds_read_b64_tr_b16 v[202:203], v213 offset:25088
	ds_read_b64_tr_b16 v[204:205], v213 offset:27136
	s_waitcnt lgkmcnt(12)
	v_mfma_f32_32x32x16_bf16 v[50:65], v[130:133], v[146:149], v[50:65]
	ds_read_b64_tr_b16 v[206:207], v213 offset:29184
	ds_read_b64_tr_b16 v[208:209], v213 offset:31232
	s_waitcnt lgkmcnt(12)
	v_mfma_f32_32x32x16_bf16 v[50:65], v[134:137], v[150:153], v[50:65]
	ds_read_b64_tr_b16 v[146:147], v213 offset:17408
	ds_read_b64_tr_b16 v[148:149], v213 offset:19456
	s_waitcnt lgkmcnt(12)
	v_mfma_f32_32x32x16_bf16 v[50:65], v[138:141], v[154:157], v[50:65]
	ds_read_b64_tr_b16 v[150:151], v213 offset:21504
	ds_read_b64_tr_b16 v[152:153], v213 offset:23552
	s_waitcnt lgkmcnt(12)
	v_mfma_f32_32x32x16_bf16 v[50:65], v[142:145], v[158:161], v[50:65]
	ds_read_b64_tr_b16 v[154:155], v213 offset:25600
	ds_read_b64_tr_b16 v[156:157], v213 offset:27648
	s_waitcnt lgkmcnt(12)
	v_mfma_f32_32x32x16_bf16 v[34:49], v[130:133], v[194:197], v[34:49]
	ds_read_b64_tr_b16 v[158:159], v213 offset:29696
	ds_read_b64_tr_b16 v[160:161], v213 offset:31744
	s_waitcnt lgkmcnt(12)
	v_mfma_f32_32x32x16_bf16 v[34:49], v[134:137], v[198:201], v[34:49]
	ds_read_b64_tr_b16 v[194:195], v213 offset:17920
	ds_read_b64_tr_b16 v[196:197], v213 offset:19968
	s_waitcnt lgkmcnt(12)
	v_mfma_f32_32x32x16_bf16 v[34:49], v[138:141], v[202:205], v[34:49]
	ds_read_b64_tr_b16 v[198:199], v213 offset:22016
	ds_read_b64_tr_b16 v[200:201], v213 offset:24064
	s_waitcnt lgkmcnt(12)
	v_mfma_f32_32x32x16_bf16 v[34:49], v[142:145], v[206:209], v[34:49]
	ds_read_b64_tr_b16 v[202:203], v213 offset:26112
	ds_read_b64_tr_b16 v[204:205], v213 offset:28160
	s_waitcnt lgkmcnt(12)
	v_mfma_f32_32x32x16_bf16 v[18:33], v[130:133], v[146:149], v[18:33]
	ds_read_b64_tr_b16 v[206:207], v213 offset:30208
	ds_read_b64_tr_b16 v[208:209], v213 offset:32256
	s_waitcnt lgkmcnt(12)
	v_mfma_f32_32x32x16_bf16 v[18:33], v[134:137], v[150:153], v[18:33]
	s_waitcnt lgkmcnt(10)
	v_mfma_f32_32x32x16_bf16 v[18:33], v[138:141], v[154:157], v[18:33]
	s_waitcnt lgkmcnt(8)
	v_mfma_f32_32x32x16_bf16 v[18:33], v[142:145], v[158:161], v[18:33]
	s_waitcnt lgkmcnt(6)
	v_mfma_f32_32x32x16_bf16 v[2:17], v[130:133], v[194:197], v[2:17]
	s_waitcnt lgkmcnt(4)
	v_mfma_f32_32x32x16_bf16 v[2:17], v[134:137], v[198:201], v[2:17]
	s_waitcnt lgkmcnt(2)
	v_mfma_f32_32x32x16_bf16 v[2:17], v[138:141], v[202:205], v[2:17]
	s_waitcnt lgkmcnt(0)
	v_mfma_f32_32x32x16_bf16 v[2:17], v[142:145], v[206:209], v[2:17]
	s_waitcnt vmcnt(0)
	s_cmp_ge_u32 s80, s0
	s_cselect_b64 s[46:47], -1, 0
	s_and_b64 vcc, exec, s[46:47]
	s_waitcnt vmcnt(0) lgkmcnt(0)
	s_barrier
; #define SBAR() __builtin_amdgcn_sched_barrier(0)
; template <int OFF> __device__ __forceinline__ bf16x8 k_read(int a) { bf16x8 r; asm volatile("ds_read_b128 %0, %1 offset:%2" : "=&v"(r) : "v"(a), "i"(OFF) : "memory"); return r; }
; #define DPUB() do { asm volatile("s_waitcnt vmcnt(0)" ::: "memory"); __syncthreads(); } while (0)
; __device__ __forceinline__ void partialSM(f32x16& p0, f32x16& p1, float& m_reg, float& mn, float& alpha) {
;   constexpr float C = SCALE * 1.4426950408889634f;
;   float pmax = p0[0];
; #pragma unroll
;   for (int r = 1; r < 16; ++r) pmax = fmaxf(pmax, p0[r]);
; #pragma unroll
;   for (int r = 0; r < 16; ++r) pmax = fmaxf(pmax, p1[r]);
;   { auto rr = __builtin_amdgcn_permlane32_swap(__float_as_uint(pmax), __float_as_uint(pmax), false, false);
;     pmax = fmaxf(__uint_as_float(rr[0]), __uint_as_float(rr[1])); }
;   if (__builtin_expect(__all(pmax - m_reg <= THR / SCALE), 1)) { mn = m_reg; alpha = 1.f; }
;   else { mn = fmaxf(m_reg, pmax); alpha = __builtin_amdgcn_exp2f((m_reg - mn) * C); m_reg = mn; }
; template <int BUFOFF, int D0> __device__ __forceinline__ void qk_step(f32x16& p0, f32x16& p1, int ka0, const bf16x8 (&qr)[8], bf16x8 (&k0)[2], bf16x8 (&k1)[2]) {
;   if constexpr (D0 + 1 < 8) { const int a_ = ka0 ^ ((D0 + 1) << 5); k0[(D0 + 1) & 1] = k_read<BUFOFF>(a_); k1[(D0 + 1) & 1] = k_read<BUFOFF + 8192>(a_); }
;   if constexpr (D0 + 1 < 8) asm volatile("s_waitcnt lgkmcnt(2)" ::: "memory"); else asm volatile("s_waitcnt lgkmcnt(0)" ::: "memory");
;   SBAR();
;   p0 = __builtin_amdgcn_mfma_f32_32x32x16_bf16(k0[D0 & 1], qr[D0], p0, 0, 0, 0);
;   p1 = __builtin_amdgcn_mfma_f32_32x32x16_bf16(k1[D0 & 1], qr[D0], p1, 0, 0, 0);
;   SBAR();
;   if constexpr (D0 + 1 < 8) qk_step<BUFOFF, (D0 + 1 < 8 ? D0 + 1 : 7)>(p0, p1, ka0, qr, k0, k1);
; }
; template <int BUFOFF> __device__ __forceinline__ void qkt_rolling(f32x16& p0, f32x16& p1, int ka0, const bf16x8 (&qr)[8]) {
;   bf16x8 k0[2], k1[2];
;   asm volatile("s_waitcnt lgkmcnt(0)" ::: "memory");
;   k0[0] = k_read<BUFOFF>(ka0); k1[0] = k_read<BUFOFF + 8192>(ka0);
;   qk_step<BUFOFF, 0>(p0, p1, ka0, qr, k0, k1);
; }
; __device__ __forceinline__ void unit_body_da(const Unit& U, char* lds) {
;     ...
;   for (int j = 0; j < NT; j += 2) {
;     DDMA(j + 1, 1); SBAR();
;     DTILE(0); SBAR(); DPUB();
;     if (j + 2 < NT) DDMA(j + 2, 0); SBAR();
;     DTILE(1); SBAR(); DPUB();
;   }
.LBB0_436:
	s_setprio 1
	s_waitcnt lgkmcnt(0)
	ds_read_b128 v[194:197], v235 offset:16384
	ds_read_b128 v[198:201], v236 offset:16384
	ds_read_b128 v[202:205], v238 offset:16384
	ds_read_b128 v[206:209], v239 offset:16384
	ds_read_b128 v[130:133], v240 offset:16384
	ds_read_b128 v[134:137], v241 offset:16384
	ds_read_b128 v[138:141], v242 offset:16384
	ds_read_b128 v[142:145], v243 offset:16384
	v_lshl_add_u64 v[232:233], v[224:225], 0, s[14:15]
	s_mov_b32 m0, s28
	s_nop 0
	global_load_lds_dwordx4 v[232:233], off
	v_lshl_add_u64 v[232:233], v[228:229], 0, s[14:15]
	s_mov_b32 m0, s67
	s_nop 0
	global_load_lds_dwordx4 v[232:233], off
	s_waitcnt lgkmcnt(7)
	s_nop 0
	v_mfma_f32_32x32x16_bf16 v[146:161], v[194:197], v[162:165], 0
	ds_read_b128 v[194:197], v235 offset:24576
	s_waitcnt lgkmcnt(7)
	v_mfma_f32_32x32x16_bf16 v[146:161], v[198:201], v[166:169], v[146:161]
	ds_read_b128 v[198:201], v236 offset:24576
	s_waitcnt lgkmcnt(7)
	v_mfma_f32_32x32x16_bf16 v[146:161], v[202:205], v[170:173], v[146:161]
	ds_read_b128 v[202:205], v238 offset:24576
	s_waitcnt lgkmcnt(7)
	v_mfma_f32_32x32x16_bf16 v[146:161], v[206:209], v[174:177], v[146:161]
	ds_read_b128 v[206:209], v239 offset:24576
	s_waitcnt lgkmcnt(7)
	v_mfma_f32_32x32x16_bf16 v[146:161], v[130:133], v[178:181], v[146:161]
	s_waitcnt lgkmcnt(6)
	v_mfma_f32_32x32x16_bf16 v[146:161], v[134:137], v[182:185], v[146:161]
	s_waitcnt lgkmcnt(5)
	v_mfma_f32_32x32x16_bf16 v[146:161], v[138:141], v[186:189], v[146:161]
	s_waitcnt lgkmcnt(4)
	v_mfma_f32_32x32x16_bf16 v[146:161], v[142:145], v[190:193], v[146:161]
	s_waitcnt lgkmcnt(3)
	v_mfma_f32_32x32x16_bf16 v[130:145], v[194:197], v[162:165], 0
	ds_read_b128 v[194:197], v240 offset:24576
	s_waitcnt lgkmcnt(3)
	v_mfma_f32_32x32x16_bf16 v[130:145], v[198:201], v[166:169], v[130:145]
	ds_read_b128 v[198:201], v241 offset:24576
	s_waitcnt lgkmcnt(3)
	v_mfma_f32_32x32x16_bf16 v[130:145], v[202:205], v[170:173], v[130:145]
	ds_read_b128 v[202:205], v242 offset:24576
	s_waitcnt lgkmcnt(3)
	v_mfma_f32_32x32x16_bf16 v[130:145], v[206:209], v[174:177], v[130:145]
	ds_read_b128 v[206:209], v243 offset:24576
	s_waitcnt lgkmcnt(3)
	v_mfma_f32_32x32x16_bf16 v[130:145], v[194:197], v[178:181], v[130:145]
	s_waitcnt lgkmcnt(2)
	v_mfma_f32_32x32x16_bf16 v[130:145], v[198:201], v[182:185], v[130:145]
	s_waitcnt lgkmcnt(1)
	v_mfma_f32_32x32x16_bf16 v[130:145], v[202:205], v[186:189], v[130:145]
	s_waitcnt lgkmcnt(0)
	v_mfma_f32_32x32x16_bf16 v[130:145], v[206:209], v[190:193], v[130:145]
	s_nop 10
	v_max_f32_e32 v194, v147, v147
	v_max_f32_e32 v195, v146, v146
	v_max_f32_e32 v194, v195, v194
	v_max3_f32 v194, v194, v148, v149
	v_max3_f32 v194, v194, v150, v151
	v_max3_f32 v194, v194, v152, v153
	v_max3_f32 v194, v194, v154, v155
	v_max3_f32 v194, v194, v156, v157
	v_max3_f32 v194, v194, v158, v159
	v_max3_f32 v194, v194, v160, v161
	v_max3_f32 v194, v194, v130, v131
	v_max3_f32 v194, v194, v132, v133
	v_max3_f32 v194, v194, v134, v135
	v_max3_f32 v194, v194, v136, v137
	v_max3_f32 v194, v194, v138, v139
	v_max3_f32 v194, v194, v140, v141
	v_max3_f32 v194, v194, v142, v143
	v_max3_f32 v194, v194, v144, v145
	v_mov_b32_e32 v195, v194
	s_nop 1
	v_permlane32_swap_b32_e32 v194, v195
	v_max_f32_e32 v195, v195, v195
	v_max_f32_e32 v194, v194, v194
	v_max_f32_e32 v194, v194, v195
	v_sub_f32_e32 v195, v194, v246
	v_cmp_ge_f32_e32 vcc, s63, v195
	v_max_f32_e32 v195, v246, v246
	v_max_f32_e32 v223, v195, v194
	v_sub_f32_e32 v194, v246, v223
	v_mul_f32_e32 v194, 0x3e0293ee, v194
	v_exp_f32_e32 v194, v194
	s_cmp_eq_u64 vcc, exec
	s_cselect_b64 s[6:7], -1, 0
	v_cndmask_b32_e64 v222, v194, 1.0, s[6:7]
	v_cmp_gt_f32_e32 vcc, 1.0, v222
	s_cbranch_vccz .LBB0_429
	s_and_saveexec_b64 s[58:59], s[4:5]
	s_cbranch_execz .LBB0_428
	ds_write_b32 v237, v222 offset:128
	s_branch .LBB0_428
.LBB0_439:
	s_setprio 0
	s_cmp_lt_u32 s25, 0x2000
	s_cbranch_scc0 .Lda_l0_lag_out
	s_barrier

; __device__ __forceinline__ int v_rd_base(int lane) { return ((lane & 3) << 3) | (((lane >> 2) & 3) << 6) | (((lane >> 4) & 1) << 5) | (((lane >> 5) & 1) << 8); }
; #define DPUB() do { asm volatile("s_waitcnt vmcnt(0)" ::: "memory"); __syncthreads(); } while (0)
; __device__ __forceinline__ void unit_body_da(const Unit& U, char* lds) {
;   int tid = threadIdx.x; asm volatile("" : "+v"(tid)); const int wid = __builtin_amdgcn_readfirstlane(tid >> 6), lane = tid & 63, r32 = lane & 31, hi = lane >> 5;
;   char* V_lds = lds; char* K_lds = lds + 2 * DA_VB;
;   float* ws = (float*)(lds + DA_WS_OFF) + wid * 64; float* li_l = ws; float* al_l = ws + 32;
;   float m_reg = -1e30f, l_reg = 0; f32x16 o[8] = {}; bf16x8 qr[8];
;   const bf16_t* Qw = U.Q + (long)(wid * QBLK + r32) * LDP + hi * 8;
; #pragma unroll
;   for (int d0 = 0; d0 < 8; ++d0) qr[d0] = ld8(Qw + d0 * 16);
;   const int vb0 = (int)(uintptr_t)V_lds + v_rd_base(lane);
;   const int ka0 = (int)(uintptr_t)K_lds + KSWZ(r32, hi * 16);
;   constexpr float C = SCALE * 1.4426950408889634f;
;   unsigned koff[2], voff[2][2];
; #pragma unroll
;   for (int i = 0; i < 2; ++i) { const int ob = (2 * wid + i) * 1024 + lane * 16;
;     { const int row = ob >> 8, cpos = (ob >> 4) & 15, c = cpos ^ (row & 7); koff[i] = (unsigned)(row * LDP + c * 8); }
;     { const int st = ob >> 9, kk = (st >> 2) * 8 + ((ob >> 6) & 7), c = (st & 3) * 32 + ((ob >> 1) & 31), k = (kk & ~0xC) | ((kk & 4) << 1) | ((kk & 8) >> 1);
;       voff[0][i] = (unsigned)(k * LDP + c); voff[1][i] = (unsigned)(k * LDP + 128 + c); } }
;   typedef __attribute__((address_space(3))) unsigned lds_u32;
;     ...
;   const int NT = U.nt;
;   DDMA(0, 0); DPUB();
;   for (int j = 0; j < NT; j += 2) {
.LBB0_1432:
	s_and_b64 vcc, exec, s[62:63]
	s_cbranch_vccz .LBB0_1404
	v_mov_b32_e32 v8, v210
	v_mov_b64_e32 v[2:3], s[56:57]
	v_readfirstlane_b32 s0, v8
	s_ashr_i32 s3, s0, 6
	s_and_b32 s0, s0, 0x3fffffc0
	s_lshl_b32 s0, s0, 2
	v_and_b32_e32 v234, 31, v8
	s_add_i32 s28, s0, 0
	s_lshl_b32 s60, s3, 5
	v_bfe_u32 v233, v8, 5, 1
	s_add_i32 s28, s28, 0x18000
	v_or_b32_e32 v0, s60, v234
	s_add_i32 s67, 0, 0x10000
	v_mad_i64_i32 v[2:3], s[0:1], v0, s92, v[2:3]
	v_lshlrev_b32_e32 v212, 4, v233
	v_mov_b32_e32 v213, v1
	s_cmp_lg_u32 s67, -1
	v_lshl_add_u64 v[2:3], v[2:3], 0, v[212:213]
	s_cselect_b32 s0, s67, 0
	s_lshl_b32 s29, s3, 11
	global_load_dwordx4 v[162:165], v[2:3], off
	global_load_dwordx4 v[166:169], v[2:3], off offset:32
	global_load_dwordx4 v[170:173], v[2:3], off offset:64
	global_load_dwordx4 v[174:177], v[2:3], off offset:96
	global_load_dwordx4 v[178:181], v[2:3], off offset:128
	global_load_dwordx4 v[182:185], v[2:3], off offset:160
	global_load_dwordx4 v[186:189], v[2:3], off offset:192
	global_load_dwordx4 v[190:193], v[2:3], off offset:224
	s_ashr_i32 s1, s29, 8
	v_lshrrev_b32_e32 v2, 1, v8
	v_and_b32_e32 v9, 63, v8
	v_bfe_u32 v0, v8, 2, 2
	s_and_b32 s3, s1, 0xfffff0
	v_and_b32_e32 v2, 8, v2
	s_waitcnt vmcnt(0)
	v_lshlrev_b32_e32 v12, 4, v9
	s_lshr_b32 s1, s1, 1
	v_or3_b32 v0, v2, v0, s3
	v_and_or_b32 v0, s1, 4, v0
	v_or_b32_e32 v5, 0x400, v12
	v_mul_i32_i24_e32 v13, 0x1800, v0
	v_or_b32_e32 v0, s29, v12
	v_or_b32_e32 v4, s29, v5
	v_and_b32_e32 v3, 15, v8
	v_ashrrev_i32_e32 v0, 8, v0
	v_ashrrev_i32_e32 v4, 8, v4
	v_bitop3_b32 v2, v0, v3, 3 bitop3:0x6c
	v_bitop3_b32 v3, v4, v3, 7 bitop3:0x6c
	v_mul_i32_i24_e32 v4, 0x1800, v4
	v_lshlrev_b32_e32 v10, 3, v9
	v_mul_i32_i24_e32 v0, 0x1800, v0
	v_lshl_or_b32 v4, v3, 3, v4
	v_lshrrev_b32_e32 v3, 4, v5
	v_and_b32_e32 v11, 24, v10
	v_lshl_or_b32 v0, v2, 3, v0
	v_and_b32_e32 v14, 32, v8
	v_and_b32_e32 v3, 0x60, v3
	s_add_i32 s61, s67, s29
	v_or3_b32 v2, v11, v14, v13
	v_or3_b32 v6, v11, v3, v13
	v_lshl_add_u64 v[214:215], v[0:1], 1, s[24:25]
	s_mov_b32 m0, s61
	v_mov_b32_e32 v3, v1
	s_add_i32 s62, s29, 0
	global_load_lds_dwordx4 v[214:215], off
	v_lshl_add_u64 v[2:3], v[2:3], 1, s[22:23]
	s_mov_b32 m0, s62
	s_add_i32 s63, s62, 0x4000
	s_or_b32 s66, s29, 0x400
	global_load_lds_dwordx4 v[2:3], off
	v_lshl_add_u64 v[2:3], v[2:3], 0, s[8:9]
	s_mov_b32 m0, s63
	v_mov_b32_e32 v5, v1
	s_add_i32 s67, s67, s66
	global_load_lds_dwordx4 v[2:3], off
	v_lshl_add_u64 v[216:217], v[4:5], 1, s[24:25]
	s_mov_b32 m0, s67
	v_mov_b32_e32 v7, v1
	s_add_i32 s68, s62, 0x400
	global_load_lds_dwordx4 v[216:217], off
	v_lshl_add_u64 v[2:3], v[6:7], 1, s[22:23]
	s_mov_b32 m0, s68
	s_add_i32 s69, s62, 0x4400
	global_load_lds_dwordx4 v[2:3], off
	v_lshl_add_u64 v[2:3], v[2:3], 0, s[8:9]
	s_mov_b32 m0, s69
	v_lshlrev_b32_e32 v0, 1, v8
	global_load_lds_dwordx4 v[2:3], off
	v_and_b32_e32 v0, 32, v0
	v_and_or_b32 v0, v12, s93, v0
	v_and_b32_e32 v2, 0x100, v10
	s_cmp_lg_u32 0, -1
	v_or3_b32 v0, v0, v2, v11
	s_cselect_b32 s3, 0, 0
	v_add_u32_e32 v213, s3, v0
	s_add_i32 s3, s3, 0x8000
	v_add_u32_e32 v244, s3, v0
	v_or3_b32 v0, v13, v14, v11
	s_movk_i32 s3, 0x60
	v_bitop3_b32 v3, v233, v8, 7 bitop3:0x78
	v_lshl_add_u64 v[218:219], v[0:1], 1, s[22:23]
	v_bitop3_b32 v0, v9, s3, 64 bitop3:0xc8
	v_lshlrev_b32_e32 v2, 8, v234
	v_lshlrev_b32_e32 v3, 4, v3
	v_or3_b32 v0, v13, v0, v11
	v_mov_b32_e32 v14, v1
	v_mov_b32_e32 v15, v1
	v_add3_u32 v235, v2, s0, v3
	s_waitcnt vmcnt(0)
	v_cmp_gt_u32_e64 s[0:1], 32, v9
	v_lshl_add_u64 v[220:221], v[0:1], 1, s[22:23]
	v_mov_b32_e32 v0, v1
	v_mov_b32_e32 v2, v1
	v_mov_b32_e32 v3, v1
	v_mov_b32_e32 v4, v1
	v_mov_b32_e32 v6, v1
	v_mov_b32_e32 v8, v1
	v_mov_b32_e32 v9, v1
	v_mov_b32_e32 v10, v1
	v_mov_b32_e32 v11, v1
	v_mov_b32_e32 v12, v1
	v_mov_b32_e32 v13, v1
	v_mov_b64_e32 v[128:129], v[14:15]
	v_mov_b64_e32 v[112:113], v[14:15]
	v_mov_b64_e32 v[96:97], v[14:15]
	v_mov_b64_e32 v[80:81], v[14:15]
	v_mov_b64_e32 v[64:65], v[14:15]
	v_mov_b64_e32 v[48:49], v[14:15]
	v_mov_b64_e32 v[32:33], v[14:15]
	v_mov_b64_e32 v[126:127], v[12:13]
	v_mov_b64_e32 v[124:125], v[10:11]
	v_mov_b64_e32 v[122:123], v[8:9]
	v_mov_b64_e32 v[120:121], v[6:7]
	v_mov_b64_e32 v[118:119], v[4:5]
	v_mov_b64_e32 v[116:117], v[2:3]
	v_mov_b64_e32 v[114:115], v[0:1]
	v_mov_b64_e32 v[110:111], v[12:13]
	v_mov_b64_e32 v[108:109], v[10:11]
	v_mov_b64_e32 v[106:107], v[8:9]
	v_mov_b64_e32 v[104:105], v[6:7]
	v_mov_b64_e32 v[102:103], v[4:5]
	v_mov_b64_e32 v[100:101], v[2:3]
	v_mov_b64_e32 v[98:99], v[0:1]
	v_mov_b64_e32 v[94:95], v[12:13]
	v_mov_b64_e32 v[92:93], v[10:11]
	v_mov_b64_e32 v[90:91], v[8:9]
	v_mov_b64_e32 v[88:89], v[6:7]
	v_mov_b64_e32 v[86:87], v[4:5]
	v_mov_b64_e32 v[84:85], v[2:3]
	v_mov_b64_e32 v[82:83], v[0:1]
	v_mov_b64_e32 v[78:79], v[12:13]
	v_mov_b64_e32 v[76:77], v[10:11]
	v_mov_b64_e32 v[74:75], v[8:9]
	v_mov_b64_e32 v[72:73], v[6:7]
	v_mov_b64_e32 v[70:71], v[4:5]
	v_mov_b64_e32 v[68:69], v[2:3]
	v_mov_b64_e32 v[66:67], v[0:1]
	v_mov_b64_e32 v[62:63], v[12:13]
	v_mov_b64_e32 v[60:61], v[10:11]
	v_mov_b64_e32 v[58:59], v[8:9]
	v_mov_b64_e32 v[56:57], v[6:7]
	v_mov_b64_e32 v[54:55], v[4:5]
	v_mov_b64_e32 v[52:53], v[2:3]
	v_mov_b64_e32 v[50:51], v[0:1]
	v_mov_b64_e32 v[46:47], v[12:13]
	v_mov_b64_e32 v[44:45], v[10:11]
	v_mov_b64_e32 v[42:43], v[8:9]
	v_mov_b64_e32 v[40:41], v[6:7]
	v_mov_b64_e32 v[38:39], v[4:5]
	v_mov_b64_e32 v[36:37], v[2:3]
	v_mov_b64_e32 v[34:35], v[0:1]
	v_mov_b64_e32 v[30:31], v[12:13]
	v_mov_b64_e32 v[28:29], v[10:11]
	v_mov_b64_e32 v[26:27], v[8:9]
	v_mov_b64_e32 v[24:25], v[6:7]
	v_mov_b64_e32 v[22:23], v[4:5]
	v_mov_b64_e32 v[20:21], v[2:3]
	v_mov_b64_e32 v[18:19], v[0:1]
	v_mov_b64_e32 v[16:17], v[14:15]
	s_mov_b32 s80, 2
	v_xor_b32_e32 v236, 32, v235
	v_xor_b32_e32 v238, 64, v235
	v_xor_b32_e32 v239, 0x60, v235
	v_xor_b32_e32 v240, 0x80, v235
	v_xor_b32_e32 v241, 0xa0, v235
	v_xor_b32_e32 v242, 0xc0, v235
	v_xor_b32_e32 v243, 0xe0, v235
	v_lshl_add_u32 v237, v234, 2, s28
	v_mov_b32_e32 v245, 0
	v_mov_b32_e32 v246, 0xf149f2ca
	s_mov_b64 s[22:23], 0
	v_mov_b64_e32 v[14:15], v[12:13]
	v_mov_b64_e32 v[12:13], v[10:11]
	v_mov_b64_e32 v[10:11], v[8:9]
	v_mov_b64_e32 v[8:9], v[6:7]
	v_mov_b64_e32 v[6:7], v[4:5]
	v_mov_b64_e32 v[4:5], v[2:3]
	v_mov_b64_e32 v[2:3], v[0:1]
	s_waitcnt vmcnt(0) lgkmcnt(0)
	s_barrier
	s_cmp_lt_u32 s29, 0x2000
	s_cbranch_scc1 .Lda_l1_lead_in
	s_barrier
; __device__ __forceinline__ void partialSM(f32x16& p0, f32x16& p1, float& m_reg, float& mn, float& alpha) {
;     ...
;   float mnC = -mn * C;
; #pragma unroll
;   for (int r = 0; r < 16; ++r) p0[r] = fmaf(p0[r], C, mnC);
; #pragma unroll
;   for (int r = 0; r < 16; ++r) p1[r] = fmaf(p1[r], C, mnC);
; #pragma unroll
;   for (int r = 0; r < 16; ++r) p0[r] = __builtin_amdgcn_exp2f(p0[r]);
; }
; __device__ __forceinline__ void finishSM(f32x16& p0, f32x16& p1, float alpha, float& l_reg, bf16x8& pa0, bf16x8& pa1, bf16x8& pa2, bf16x8& pa3) {
; #pragma unroll
;   for (int r = 0; r < 16; ++r) p1[r] = __builtin_amdgcn_exp2f(p1[r]);
;   float ps = 0;
; #pragma unroll
;   for (int r = 0; r < 16; ++r) ps += p0[r];
; #pragma unroll
;   for (int r = 0; r < 16; ++r) ps += p1[r];
;   { auto rr = __builtin_amdgcn_permlane32_swap(__float_as_uint(ps), __float_as_uint(ps), false, false);
;     ps = __uint_as_float(rr[0]) + __uint_as_float(rr[1]); }
;   l_reg = l_reg * alpha + ps;
.Lda_l1_lead_in:
	s_branch .LBB0_1436
.LBB0_1434:
	s_or_b64 exec, exec, s[56:57]
	s_waitcnt lgkmcnt(0)
	v_add_u32_e32 v194, s28, v212
	ds_read_b128 v[206:209], v194 offset:224
	ds_read_b128 v[202:205], v194 offset:192
	ds_read_b128 v[198:201], v194 offset:160
	ds_read_b128 v[194:197], v194 offset:128
	s_waitcnt lgkmcnt(0)
	v_pk_mul_f32 v[126:127], v[126:127], v[206:207]
	v_pk_mul_f32 v[122:123], v[122:123], v[202:203]
	v_pk_mul_f32 v[118:119], v[118:119], v[198:199]
	v_pk_mul_f32 v[128:129], v[128:129], v[208:209]
	v_pk_mul_f32 v[124:125], v[124:125], v[204:205]
	v_pk_mul_f32 v[120:121], v[120:121], v[200:201]
	v_pk_mul_f32 v[116:117], v[116:117], v[196:197]
	v_pk_mul_f32 v[114:115], v[114:115], v[194:195]
	v_pk_mul_f32 v[110:111], v[110:111], v[206:207]
	v_pk_mul_f32 v[106:107], v[106:107], v[202:203]
	v_pk_mul_f32 v[102:103], v[102:103], v[198:199]
	v_pk_mul_f32 v[112:113], v[112:113], v[208:209]
	v_pk_mul_f32 v[108:109], v[108:109], v[204:205]
	v_pk_mul_f32 v[104:105], v[104:105], v[200:201]
	v_pk_mul_f32 v[100:101], v[100:101], v[196:197]
	v_pk_mul_f32 v[98:99], v[98:99], v[194:195]
	v_pk_mul_f32 v[94:95], v[94:95], v[206:207]
	v_pk_mul_f32 v[90:91], v[90:91], v[202:203]
	v_pk_mul_f32 v[86:87], v[86:87], v[198:199]
	v_pk_mul_f32 v[96:97], v[96:97], v[208:209]
	v_pk_mul_f32 v[92:93], v[92:93], v[204:205]
	v_pk_mul_f32 v[88:89], v[88:89], v[200:201]
	v_pk_mul_f32 v[84:85], v[84:85], v[196:197]
	v_pk_mul_f32 v[82:83], v[82:83], v[194:195]
	v_pk_mul_f32 v[78:79], v[78:79], v[206:207]
	v_pk_mul_f32 v[74:75], v[74:75], v[202:203]
	v_pk_mul_f32 v[70:71], v[70:71], v[198:199]
	v_pk_mul_f32 v[80:81], v[80:81], v[208:209]
	v_pk_mul_f32 v[76:77], v[76:77], v[204:205]
	v_pk_mul_f32 v[72:73], v[72:73], v[200:201]
	v_pk_mul_f32 v[68:69], v[68:69], v[196:197]
	v_pk_mul_f32 v[66:67], v[66:67], v[194:195]
	v_pk_mul_f32 v[62:63], v[62:63], v[206:207]
	v_pk_mul_f32 v[58:59], v[58:59], v[202:203]
	v_pk_mul_f32 v[54:55], v[54:55], v[198:199]
	v_pk_mul_f32 v[64:65], v[64:65], v[208:209]
	v_pk_mul_f32 v[60:61], v[60:61], v[204:205]
	v_pk_mul_f32 v[56:57], v[56:57], v[200:201]
	v_pk_mul_f32 v[52:53], v[52:53], v[196:197]
	v_pk_mul_f32 v[50:51], v[50:51], v[194:195]
	v_pk_mul_f32 v[46:47], v[46:47], v[206:207]
	v_pk_mul_f32 v[42:43], v[42:43], v[202:203]
	v_pk_mul_f32 v[38:39], v[38:39], v[198:199]
	v_pk_mul_f32 v[48:49], v[48:49], v[208:209]
	v_pk_mul_f32 v[44:45], v[44:45], v[204:205]
	v_pk_mul_f32 v[40:41], v[40:41], v[200:201]
	v_pk_mul_f32 v[36:37], v[36:37], v[196:197]
	v_pk_mul_f32 v[34:35], v[34:35], v[194:195]
	v_pk_mul_f32 v[30:31], v[30:31], v[206:207]
	v_pk_mul_f32 v[26:27], v[26:27], v[202:203]
	v_pk_mul_f32 v[22:23], v[22:23], v[198:199]
	v_pk_mul_f32 v[32:33], v[32:33], v[208:209]
	v_pk_mul_f32 v[28:29], v[28:29], v[204:205]
	v_pk_mul_f32 v[24:25], v[24:25], v[200:201]
	v_pk_mul_f32 v[20:21], v[20:21], v[196:197]
	v_pk_mul_f32 v[18:19], v[18:19], v[194:195]
	v_pk_mul_f32 v[14:15], v[14:15], v[206:207]
	v_pk_mul_f32 v[10:11], v[10:11], v[202:203]
	v_pk_mul_f32 v[6:7], v[6:7], v[198:199]
	v_pk_mul_f32 v[16:17], v[16:17], v[208:209]
	v_pk_mul_f32 v[12:13], v[12:13], v[204:205]
	v_pk_mul_f32 v[8:9], v[8:9], v[200:201]
	v_pk_mul_f32 v[4:5], v[4:5], v[196:197]
	v_pk_mul_f32 v[2:3], v[2:3], v[194:195]
.LBB0_1435:
	v_cndmask_b32_e64 v246, v223, v246, s[6:7]
	v_mul_f32_e32 v194, 0xbe0293ee, v246
	v_fmamk_f32 v146, v146, 0x3e0293ee, v194
	v_fmamk_f32 v147, v147, 0x3e0293ee, v194
	v_fmamk_f32 v148, v148, 0x3e0293ee, v194
	v_fmamk_f32 v149, v149, 0x3e0293ee, v194
	v_fmamk_f32 v150, v150, 0x3e0293ee, v194
	v_fmamk_f32 v151, v151, 0x3e0293ee, v194
	v_fmamk_f32 v152, v152, 0x3e0293ee, v194
	v_fmamk_f32 v153, v153, 0x3e0293ee, v194
	v_fmamk_f32 v154, v154, 0x3e0293ee, v194
	v_fmamk_f32 v155, v155, 0x3e0293ee, v194
	v_fmamk_f32 v156, v156, 0x3e0293ee, v194
	v_fmamk_f32 v157, v157, 0x3e0293ee, v194
	v_fmamk_f32 v158, v158, 0x3e0293ee, v194
	v_fmamk_f32 v159, v159, 0x3e0293ee, v194
	v_fmamk_f32 v160, v160, 0x3e0293ee, v194
	v_fmamk_f32 v161, v161, 0x3e0293ee, v194
	v_fmamk_f32 v130, v130, 0x3e0293ee, v194
	v_fmamk_f32 v131, v131, 0x3e0293ee, v194
	v_fmamk_f32 v132, v132, 0x3e0293ee, v194
	v_fmamk_f32 v133, v133, 0x3e0293ee, v194
	v_fmamk_f32 v134, v134, 0x3e0293ee, v194
	v_fmamk_f32 v135, v135, 0x3e0293ee, v194
	v_fmamk_f32 v136, v136, 0x3e0293ee, v194
	v_fmamk_f32 v137, v137, 0x3e0293ee, v194
	v_fmamk_f32 v138, v138, 0x3e0293ee, v194
	v_fmamk_f32 v139, v139, 0x3e0293ee, v194
	v_fmamk_f32 v140, v140, 0x3e0293ee, v194
	v_fmamk_f32 v141, v141, 0x3e0293ee, v194
	v_fmamk_f32 v142, v142, 0x3e0293ee, v194
	v_fmamk_f32 v143, v143, 0x3e0293ee, v194
	v_fmamk_f32 v144, v144, 0x3e0293ee, v194
	v_fmac_f32_e32 v194, 0x3e0293ee, v145
	v_exp_f32_e32 v145, v146
	v_exp_f32_e32 v146, v147
	v_exp_f32_e32 v147, v148
	v_exp_f32_e32 v148, v149
	v_exp_f32_e32 v149, v150
	v_exp_f32_e32 v150, v151
	v_exp_f32_e32 v151, v152
	v_exp_f32_e32 v152, v153
	v_exp_f32_e32 v153, v154
	v_exp_f32_e32 v154, v155
	v_exp_f32_e32 v155, v156
	v_exp_f32_e32 v156, v157
	v_exp_f32_e32 v157, v158
	v_exp_f32_e32 v158, v159
	v_exp_f32_e32 v159, v160
	v_exp_f32_e32 v160, v161
	v_add_f32_e32 v161, v247, v248
	v_fmac_f32_e32 v161, v245, v0
	v_exp_f32_e32 v0, v130
	v_add_f32_e32 v130, 0, v145
	v_add_f32_e32 v130, v146, v130
	v_add_f32_e32 v130, v147, v130
	v_add_f32_e32 v130, v148, v130
	v_add_f32_e32 v130, v149, v130
	v_add_f32_e32 v130, v150, v130
	v_add_f32_e32 v130, v151, v130
	v_add_f32_e32 v130, v152, v130
	v_add_f32_e32 v130, v153, v130
	v_add_f32_e32 v130, v154, v130
	v_add_f32_e32 v130, v155, v130
	v_add_f32_e32 v130, v156, v130
	v_add_f32_e32 v130, v157, v130
	v_exp_f32_e32 v195, v131
; #define SBAR() __builtin_amdgcn_sched_barrier(0)
; __device__ __forceinline__ void finishSM(f32x16& p0, f32x16& p1, float alpha, float& l_reg, bf16x8& pa0, bf16x8& pa1, bf16x8& pa2, bf16x8& pa3) {
;     ...
;   for (int r = 0; r < 16; ++r) p1[r] = __builtin_amdgcn_exp2f(p1[r]);
;   float ps = 0;
; #pragma unroll
;   for (int r = 0; r < 16; ++r) ps += p0[r];
; #pragma unroll
;   for (int r = 0; r < 16; ++r) ps += p1[r];
;   { auto rr = __builtin_amdgcn_permlane32_swap(__float_as_uint(ps), __float_as_uint(ps), false, false);
;     ps = __uint_as_float(rr[0]) + __uint_as_float(rr[1]); }
;   l_reg = l_reg * alpha + ps;
;     ...
;   PK4(p0, 0, pa0); PK4(p0, 8, pa1); PK4(p1, 0, pa2); PK4(p1, 8, pa3);
; template <int I> __device__ __forceinline__ void pv_step(f32x16* o, int vb, const bf16x8 (&pa)[4], s16x4 (&l)[3], s16x4 (&h)[3]) {
;   if constexpr (I + 2 < 32) pv_rd<(I + 2 < 32 ? I + 2 : 0)>(vb, l[(I + 2) % 3], h[(I + 2) % 3]);
;   if constexpr (I + 2 < 32) asm volatile("s_waitcnt lgkmcnt(4)" ::: "memory"); else if constexpr (I + 1 < 32) asm volatile("s_waitcnt lgkmcnt(2)" ::: "memory"); else asm volatile("s_waitcnt lgkmcnt(0)" ::: "memory");
;   SBAR();
;   const s16x4 L = l[I % 3], H = h[I % 3];
;   o[I >> 2] = __builtin_amdgcn_mfma_f32_32x32x16_bf16(pa[I & 3], (bf16x8){L[0], L[1], L[2], L[3], H[0], H[1], H[2], H[3]}, o[I >> 2], 0, 0, 0);
;   SBAR();
;   if constexpr (I + 1 < 32) pv_step<(I + 1 < 32 ? I + 1 : 31)>(o, vb, pa, l, h);
; }
; __device__ __forceinline__ void pv_all_rolling(f32x16* o, int vb, bf16x8 pa0, bf16x8 pa1, bf16x8 pa2, bf16x8 pa3) {
;   const bf16x8 pa[4] = {pa0, pa1, pa2, pa3}; s16x4 l[3], h[3];
;   asm volatile("s_waitcnt lgkmcnt(0)" ::: "memory");
;   pv_rd<0>(vb, l[0], h[0]); pv_rd<1>(vb, l[1], h[1]);
;   pv_step<0>(o, vb, pa, l, h);
	v_add_f32_e32 v130, v158, v130
	v_exp_f32_e32 v196, v132
	v_add_f32_e32 v130, v159, v130
	v_exp_f32_e32 v197, v133
	v_add_f32_e32 v130, v160, v130
	v_exp_f32_e32 v198, v134
	v_add_f32_e32 v130, v0, v130
	v_exp_f32_e32 v199, v135
	v_add_f32_e32 v130, v195, v130
	v_exp_f32_e32 v200, v136
	v_add_f32_e32 v130, v196, v130
	v_exp_f32_e32 v201, v137
	v_add_f32_e32 v130, v197, v130
	v_exp_f32_e32 v202, v138
	v_add_f32_e32 v130, v198, v130
	v_exp_f32_e32 v203, v139
	v_add_f32_e32 v130, v199, v130
	v_exp_f32_e32 v204, v140
	v_add_f32_e32 v130, v200, v130
	v_exp_f32_e32 v205, v141
	v_add_f32_e32 v130, v201, v130
	v_exp_f32_e32 v206, v142
	v_add_f32_e32 v130, v202, v130
	v_exp_f32_e32 v207, v143
	v_add_f32_e32 v130, v203, v130
	v_exp_f32_e32 v208, v144
	v_add_f32_e32 v130, v204, v130
	v_exp_f32_e32 v194, v194
	v_add_f32_e32 v130, v205, v130
	v_add_f32_e32 v130, v206, v130
	v_add_f32_e32 v130, v207, v130
	v_add_f32_e32 v130, v208, v130
	v_add_f32_e32 v130, v194, v130
	v_mov_b32_e32 v131, v130
	s_nop 1
	v_permlane32_swap_b32_e32 v130, v131
	v_add_f32_e32 v245, v130, v131
	v_fmac_f32_e32 v245, v161, v222
	v_cvt_pk_bf16_f32 v130, v145, v146
	v_cvt_pk_bf16_f32 v131, v147, v148
	v_cvt_pk_bf16_f32 v132, v149, v150
	v_cvt_pk_bf16_f32 v133, v151, v152
	v_cvt_pk_bf16_f32 v134, v153, v154
	v_cvt_pk_bf16_f32 v135, v155, v156
	v_cvt_pk_bf16_f32 v136, v157, v158
	v_cvt_pk_bf16_f32 v137, v159, v160
	v_cvt_pk_bf16_f32 v138, v0, v195
	v_cvt_pk_bf16_f32 v139, v196, v197
	v_cvt_pk_bf16_f32 v140, v198, v199
	v_cvt_pk_bf16_f32 v141, v200, v201
	v_cvt_pk_bf16_f32 v142, v202, v203
	v_cvt_pk_bf16_f32 v143, v204, v205
	v_cvt_pk_bf16_f32 v144, v206, v207
	v_cvt_pk_bf16_f32 v145, v208, v194
	s_nop 0
	v_permlane32_swap_b32_e32 v130, v132
	v_permlane32_swap_b32_e32 v131, v133
	v_permlane32_swap_b32_e32 v134, v136
	v_permlane32_swap_b32_e32 v135, v137
	v_permlane32_swap_b32_e32 v138, v140
	v_permlane32_swap_b32_e32 v139, v141
	v_permlane32_swap_b32_e32 v142, v144
	v_permlane32_swap_b32_e32 v143, v145
	s_waitcnt vmcnt(0)
	s_barrier
	s_setprio 0
	s_waitcnt lgkmcnt(0)
	ds_read_b64_tr_b16 v[146:147], v244 offset:0
	ds_read_b64_tr_b16 v[148:149], v244 offset:2048
	ds_read_b64_tr_b16 v[150:151], v244 offset:4096
	ds_read_b64_tr_b16 v[152:153], v244 offset:6144
	ds_read_b64_tr_b16 v[154:155], v244 offset:8192
	ds_read_b64_tr_b16 v[156:157], v244 offset:10240
	ds_read_b64_tr_b16 v[158:159], v244 offset:12288
	ds_read_b64_tr_b16 v[160:161], v244 offset:14336
	ds_read_b64_tr_b16 v[194:195], v244 offset:512
	ds_read_b64_tr_b16 v[196:197], v244 offset:2560
	ds_read_b64_tr_b16 v[198:199], v244 offset:4608
	ds_read_b64_tr_b16 v[200:201], v244 offset:6656
	ds_read_b64_tr_b16 v[202:203], v244 offset:8704
	ds_read_b64_tr_b16 v[204:205], v244 offset:10752
	v_lshl_add_u64 v[232:233], v[218:219], 0, s[22:23]
	v_lshl_add_u64 v[232:233], v[232:233], 0, s[14:15]
	s_mov_b32 m0, s62
	s_nop 0
	global_load_lds_dwordx4 v[232:233], off
	s_waitcnt lgkmcnt(12)
	s_nop 0
	v_mfma_f32_32x32x16_bf16 v[114:129], v[130:133], v[146:149], v[114:129]
	ds_read_b64_tr_b16 v[206:207], v244 offset:12800
	ds_read_b64_tr_b16 v[208:209], v244 offset:14848
	v_lshl_add_u64 v[232:233], v[218:219], 0, s[22:23]
	v_lshl_add_u64 v[232:233], v[232:233], 0, s[16:17]
	s_mov_b32 m0, s63
	s_nop 0
	global_load_lds_dwordx4 v[232:233], off
	s_waitcnt lgkmcnt(12)
	v_mfma_f32_32x32x16_bf16 v[114:129], v[134:137], v[150:153], v[114:129]
	ds_read_b64_tr_b16 v[146:147], v244 offset:1024
	ds_read_b64_tr_b16 v[148:149], v244 offset:3072
	v_lshl_add_u64 v[232:233], v[220:221], 0, s[22:23]
	v_lshl_add_u64 v[232:233], v[232:233], 0, s[14:15]
	s_mov_b32 m0, s68
	s_nop 0
	global_load_lds_dwordx4 v[232:233], off
	s_waitcnt lgkmcnt(12)
	v_mfma_f32_32x32x16_bf16 v[114:129], v[138:141], v[154:157], v[114:129]
	ds_read_b64_tr_b16 v[150:151], v244 offset:5120
	ds_read_b64_tr_b16 v[152:153], v244 offset:7168
	v_lshl_add_u64 v[232:233], v[220:221], 0, s[22:23]
	v_lshl_add_u64 v[232:233], v[232:233], 0, s[16:17]
	s_mov_b32 m0, s69
	s_nop 0
	global_load_lds_dwordx4 v[232:233], off
	s_waitcnt lgkmcnt(12)
	v_mfma_f32_32x32x16_bf16 v[114:129], v[142:145], v[158:161], v[114:129]
	ds_read_b64_tr_b16 v[154:155], v244 offset:9216
	ds_read_b64_tr_b16 v[156:157], v244 offset:11264
	s_waitcnt lgkmcnt(12)
	v_mfma_f32_32x32x16_bf16 v[98:113], v[130:133], v[194:197], v[98:113]
	ds_read_b64_tr_b16 v[158:159], v244 offset:13312
	ds_read_b64_tr_b16 v[160:161], v244 offset:15360
	s_waitcnt lgkmcnt(12)
	v_mfma_f32_32x32x16_bf16 v[98:113], v[134:137], v[198:201], v[98:113]
	ds_read_b64_tr_b16 v[194:195], v244 offset:1536
	ds_read_b64_tr_b16 v[196:197], v244 offset:3584
	s_waitcnt lgkmcnt(12)
	v_mfma_f32_32x32x16_bf16 v[98:113], v[138:141], v[202:205], v[98:113]
	ds_read_b64_tr_b16 v[198:199], v244 offset:5632
	ds_read_b64_tr_b16 v[200:201], v244 offset:7680
	s_waitcnt lgkmcnt(12)
	v_mfma_f32_32x32x16_bf16 v[98:113], v[142:145], v[206:209], v[98:113]
	ds_read_b64_tr_b16 v[202:203], v244 offset:9728
	ds_read_b64_tr_b16 v[204:205], v244 offset:11776
	s_waitcnt lgkmcnt(12)
	v_mfma_f32_32x32x16_bf16 v[82:97], v[130:133], v[146:149], v[82:97]
	ds_read_b64_tr_b16 v[206:207], v244 offset:13824
	ds_read_b64_tr_b16 v[208:209], v244 offset:15872
	s_waitcnt lgkmcnt(12)
	v_mfma_f32_32x32x16_bf16 v[82:97], v[134:137], v[150:153], v[82:97]
	ds_read_b64_tr_b16 v[146:147], v244 offset:16384
	ds_read_b64_tr_b16 v[148:149], v244 offset:18432
	s_waitcnt lgkmcnt(12)
	v_mfma_f32_32x32x16_bf16 v[82:97], v[138:141], v[154:157], v[82:97]
	ds_read_b64_tr_b16 v[150:151], v244 offset:20480
	ds_read_b64_tr_b16 v[152:153], v244 offset:22528
	s_waitcnt lgkmcnt(12)
; #define SBAR() __builtin_amdgcn_sched_barrier(0)
; template <int OFF> __device__ __forceinline__ bf16x8 k_read(int a) { bf16x8 r; asm volatile("ds_read_b128 %0, %1 offset:%2" : "=&v"(r) : "v"(a), "i"(OFF) : "memory"); return r; }
; template <int I> __device__ __forceinline__ void pv_step(f32x16* o, int vb, const bf16x8 (&pa)[4], s16x4 (&l)[3], s16x4 (&h)[3]) {
;   if constexpr (I + 2 < 32) pv_rd<(I + 2 < 32 ? I + 2 : 0)>(vb, l[(I + 2) % 3], h[(I + 2) % 3]);
;   if constexpr (I + 2 < 32) asm volatile("s_waitcnt lgkmcnt(4)" ::: "memory"); else if constexpr (I + 1 < 32) asm volatile("s_waitcnt lgkmcnt(2)" ::: "memory"); else asm volatile("s_waitcnt lgkmcnt(0)" ::: "memory");
;   SBAR();
;   const s16x4 L = l[I % 3], H = h[I % 3];
;   o[I >> 2] = __builtin_amdgcn_mfma_f32_32x32x16_bf16(pa[I & 3], (bf16x8){L[0], L[1], L[2], L[3], H[0], H[1], H[2], H[3]}, o[I >> 2], 0, 0, 0);
;   SBAR();
;   if constexpr (I + 1 < 32) pv_step<(I + 1 < 32 ? I + 1 : 31)>(o, vb, pa, l, h);
; }
; __device__ __forceinline__ void pv_all_rolling(f32x16* o, int vb, bf16x8 pa0, bf16x8 pa1, bf16x8 pa2, bf16x8 pa3) {
;   const bf16x8 pa[4] = {pa0, pa1, pa2, pa3}; s16x4 l[3], h[3];
;   asm volatile("s_waitcnt lgkmcnt(0)" ::: "memory");
;   pv_rd<0>(vb, l[0], h[0]); pv_rd<1>(vb, l[1], h[1]);
;   pv_step<0>(o, vb, pa, l, h);
; template <int BUFOFF, int D0> __device__ __forceinline__ void qk_step(f32x16& p0, f32x16& p1, int ka0, const bf16x8 (&qr)[8], bf16x8 (&k0)[2], bf16x8 (&k1)[2]) {
;   if constexpr (D0 + 1 < 8) { const int a_ = ka0 ^ ((D0 + 1) << 5); k0[(D0 + 1) & 1] = k_read<BUFOFF>(a_); k1[(D0 + 1) & 1] = k_read<BUFOFF + 8192>(a_); }
;   if constexpr (D0 + 1 < 8) asm volatile("s_waitcnt lgkmcnt(2)" ::: "memory"); else asm volatile("s_waitcnt lgkmcnt(0)" ::: "memory");
;   SBAR();
;   p0 = __builtin_amdgcn_mfma_f32_32x32x16_bf16(k0[D0 & 1], qr[D0], p0, 0, 0, 0);
;   p1 = __builtin_amdgcn_mfma_f32_32x32x16_bf16(k1[D0 & 1], qr[D0], p1, 0, 0, 0);
;   SBAR();
;   if constexpr (D0 + 1 < 8) qk_step<BUFOFF, (D0 + 1 < 8 ? D0 + 1 : 7)>(p0, p1, ka0, qr, k0, k1);
; }
; template <int BUFOFF> __device__ __forceinline__ void qkt_rolling(f32x16& p0, f32x16& p1, int ka0, const bf16x8 (&qr)[8]) {
;   bf16x8 k0[2], k1[2];
;   asm volatile("s_waitcnt lgkmcnt(0)" ::: "memory");
;   k0[0] = k_read<BUFOFF>(ka0); k1[0] = k_read<BUFOFF + 8192>(ka0);
;   qk_step<BUFOFF, 0>(p0, p1, ka0, qr, k0, k1);
; }
	v_mfma_f32_32x32x16_bf16 v[82:97], v[142:145], v[158:161], v[82:97]
	ds_read_b64_tr_b16 v[154:155], v244 offset:24576
	ds_read_b64_tr_b16 v[156:157], v244 offset:26624
	s_waitcnt lgkmcnt(12)
	v_mfma_f32_32x32x16_bf16 v[66:81], v[130:133], v[194:197], v[66:81]
	ds_read_b64_tr_b16 v[158:159], v244 offset:28672
	ds_read_b64_tr_b16 v[160:161], v244 offset:30720
	s_waitcnt lgkmcnt(12)
	v_mfma_f32_32x32x16_bf16 v[66:81], v[134:137], v[198:201], v[66:81]
	ds_read_b64_tr_b16 v[194:195], v244 offset:16896
	ds_read_b64_tr_b16 v[196:197], v244 offset:18944
	s_waitcnt lgkmcnt(12)
	v_mfma_f32_32x32x16_bf16 v[66:81], v[138:141], v[202:205], v[66:81]
	ds_read_b64_tr_b16 v[198:199], v244 offset:20992
	ds_read_b64_tr_b16 v[200:201], v244 offset:23040
	s_waitcnt lgkmcnt(12)
	v_mfma_f32_32x32x16_bf16 v[66:81], v[142:145], v[206:209], v[66:81]
	ds_read_b64_tr_b16 v[202:203], v244 offset:25088
	ds_read_b64_tr_b16 v[204:205], v244 offset:27136
	s_waitcnt lgkmcnt(12)
	v_mfma_f32_32x32x16_bf16 v[50:65], v[130:133], v[146:149], v[50:65]
	ds_read_b64_tr_b16 v[206:207], v244 offset:29184
	ds_read_b64_tr_b16 v[208:209], v244 offset:31232
	s_waitcnt lgkmcnt(12)
	v_mfma_f32_32x32x16_bf16 v[50:65], v[134:137], v[150:153], v[50:65]
	ds_read_b64_tr_b16 v[146:147], v244 offset:17408
	ds_read_b64_tr_b16 v[148:149], v244 offset:19456
	s_waitcnt lgkmcnt(12)
	v_mfma_f32_32x32x16_bf16 v[50:65], v[138:141], v[154:157], v[50:65]
	ds_read_b64_tr_b16 v[150:151], v244 offset:21504
	ds_read_b64_tr_b16 v[152:153], v244 offset:23552
	s_waitcnt lgkmcnt(12)
	v_mfma_f32_32x32x16_bf16 v[50:65], v[142:145], v[158:161], v[50:65]
	ds_read_b64_tr_b16 v[154:155], v244 offset:25600
	ds_read_b64_tr_b16 v[156:157], v244 offset:27648
	s_waitcnt lgkmcnt(12)
	v_mfma_f32_32x32x16_bf16 v[34:49], v[130:133], v[194:197], v[34:49]
	ds_read_b64_tr_b16 v[158:159], v244 offset:29696
	ds_read_b64_tr_b16 v[160:161], v244 offset:31744
	s_waitcnt lgkmcnt(12)
	v_mfma_f32_32x32x16_bf16 v[34:49], v[134:137], v[198:201], v[34:49]
	ds_read_b64_tr_b16 v[194:195], v244 offset:17920
	ds_read_b64_tr_b16 v[196:197], v244 offset:19968
	s_waitcnt lgkmcnt(12)
	v_mfma_f32_32x32x16_bf16 v[34:49], v[138:141], v[202:205], v[34:49]
	ds_read_b64_tr_b16 v[198:199], v244 offset:22016
	ds_read_b64_tr_b16 v[200:201], v244 offset:24064
	s_waitcnt lgkmcnt(12)
	v_mfma_f32_32x32x16_bf16 v[34:49], v[142:145], v[206:209], v[34:49]
	ds_read_b64_tr_b16 v[202:203], v244 offset:26112
	ds_read_b64_tr_b16 v[204:205], v244 offset:28160
	s_waitcnt lgkmcnt(12)
	v_mfma_f32_32x32x16_bf16 v[18:33], v[130:133], v[146:149], v[18:33]
	ds_read_b64_tr_b16 v[206:207], v244 offset:30208
	ds_read_b64_tr_b16 v[208:209], v244 offset:32256
	s_waitcnt lgkmcnt(12)
	v_mfma_f32_32x32x16_bf16 v[18:33], v[134:137], v[150:153], v[18:33]
	s_waitcnt lgkmcnt(10)
	v_mfma_f32_32x32x16_bf16 v[18:33], v[138:141], v[154:157], v[18:33]
	s_waitcnt lgkmcnt(8)
	v_mfma_f32_32x32x16_bf16 v[18:33], v[142:145], v[158:161], v[18:33]
	s_waitcnt lgkmcnt(6)
	v_mfma_f32_32x32x16_bf16 v[2:17], v[130:133], v[194:197], v[2:17]
	s_waitcnt lgkmcnt(4)
	v_mfma_f32_32x32x16_bf16 v[2:17], v[134:137], v[198:201], v[2:17]
	s_waitcnt lgkmcnt(2)
	v_mfma_f32_32x32x16_bf16 v[2:17], v[138:141], v[202:205], v[2:17]
	s_waitcnt lgkmcnt(0)
	v_mfma_f32_32x32x16_bf16 v[2:17], v[142:145], v[206:209], v[2:17]
	s_waitcnt vmcnt(0)
	s_add_u32 s22, s22, 0x180000
	s_addc_u32 s23, s23, 0
	s_add_i32 s80, s80, 2
	s_and_b64 vcc, exec, s[24:25]
	s_waitcnt vmcnt(0) lgkmcnt(0)
	s_barrier
	s_cbranch_vccnz .LBB0_1445
.LBB0_1436:
	s_setprio 1
	v_lshl_add_u64 v[224:225], v[214:215], 0, s[22:23]
	v_lshl_add_u64 v[228:229], v[216:217], 0, s[22:23]
	s_waitcnt lgkmcnt(0)
	ds_read_b128 v[194:197], v235 offset:0
	ds_read_b128 v[198:201], v236 offset:0
	ds_read_b128 v[202:205], v238 offset:0
	ds_read_b128 v[206:209], v239 offset:0
	ds_read_b128 v[130:133], v240 offset:0
	ds_read_b128 v[134:137], v241 offset:0
	ds_read_b128 v[138:141], v242 offset:0
	ds_read_b128 v[142:145], v243 offset:0
	v_lshl_add_u64 v[232:233], v[224:225], 0, s[10:11]
	s_add_i32 m0, s94, s29
	s_nop 0
	global_load_lds_dwordx4 v[232:233], off
	v_lshl_add_u64 v[232:233], v[228:229], 0, s[10:11]
	s_add_i32 m0, s94, s66
	s_nop 0
	global_load_lds_dwordx4 v[232:233], off
	s_waitcnt lgkmcnt(7)
	s_nop 0
	v_mfma_f32_32x32x16_bf16 v[146:161], v[194:197], v[162:165], 0
	ds_read_b128 v[194:197], v235 offset:8192
	s_waitcnt lgkmcnt(7)
	v_mfma_f32_32x32x16_bf16 v[146:161], v[198:201], v[166:169], v[146:161]
	ds_read_b128 v[198:201], v236 offset:8192
	s_waitcnt lgkmcnt(7)
	v_mfma_f32_32x32x16_bf16 v[146:161], v[202:205], v[170:173], v[146:161]
	ds_read_b128 v[202:205], v238 offset:8192
	s_waitcnt lgkmcnt(7)
	v_mfma_f32_32x32x16_bf16 v[146:161], v[206:209], v[174:177], v[146:161]
	ds_read_b128 v[206:209], v239 offset:8192
	s_waitcnt lgkmcnt(7)
	v_mfma_f32_32x32x16_bf16 v[146:161], v[130:133], v[178:181], v[146:161]
	s_waitcnt lgkmcnt(6)
	v_mfma_f32_32x32x16_bf16 v[146:161], v[134:137], v[182:185], v[146:161]
	s_waitcnt lgkmcnt(5)
	v_mfma_f32_32x32x16_bf16 v[146:161], v[138:141], v[186:189], v[146:161]
	s_waitcnt lgkmcnt(4)
	v_mfma_f32_32x32x16_bf16 v[146:161], v[142:145], v[190:193], v[146:161]
	s_waitcnt lgkmcnt(3)
	v_mfma_f32_32x32x16_bf16 v[130:145], v[194:197], v[162:165], 0
	ds_read_b128 v[194:197], v240 offset:8192
	s_waitcnt lgkmcnt(3)
	v_mfma_f32_32x32x16_bf16 v[130:145], v[198:201], v[166:169], v[130:145]
	ds_read_b128 v[198:201], v241 offset:8192
	s_waitcnt lgkmcnt(3)
	v_mfma_f32_32x32x16_bf16 v[130:145], v[202:205], v[170:173], v[130:145]
	ds_read_b128 v[202:205], v242 offset:8192
	s_waitcnt lgkmcnt(3)
; #define SBAR() __builtin_amdgcn_sched_barrier(0)
; template <int OFF> __device__ __forceinline__ bf16x8 k_read(int a) { bf16x8 r; asm volatile("ds_read_b128 %0, %1 offset:%2" : "=&v"(r) : "v"(a), "i"(OFF) : "memory"); return r; }
; __device__ __forceinline__ void partialSM(f32x16& p0, f32x16& p1, float& m_reg, float& mn, float& alpha) {
;   constexpr float C = SCALE * 1.4426950408889634f;
;   float pmax = p0[0];
; #pragma unroll
;   for (int r = 1; r < 16; ++r) pmax = fmaxf(pmax, p0[r]);
; #pragma unroll
;   for (int r = 0; r < 16; ++r) pmax = fmaxf(pmax, p1[r]);
;   { auto rr = __builtin_amdgcn_permlane32_swap(__float_as_uint(pmax), __float_as_uint(pmax), false, false);
;     pmax = fmaxf(__uint_as_float(rr[0]), __uint_as_float(rr[1])); }
;   if (__builtin_expect(__all(pmax - m_reg <= THR / SCALE), 1)) { mn = m_reg; alpha = 1.f; }
;   else { mn = fmaxf(m_reg, pmax); alpha = __builtin_amdgcn_exp2f((m_reg - mn) * C); m_reg = mn; }
; template <int BUFOFF, int D0> __device__ __forceinline__ void qk_step(f32x16& p0, f32x16& p1, int ka0, const bf16x8 (&qr)[8], bf16x8 (&k0)[2], bf16x8 (&k1)[2]) {
;   if constexpr (D0 + 1 < 8) { const int a_ = ka0 ^ ((D0 + 1) << 5); k0[(D0 + 1) & 1] = k_read<BUFOFF>(a_); k1[(D0 + 1) & 1] = k_read<BUFOFF + 8192>(a_); }
;   if constexpr (D0 + 1 < 8) asm volatile("s_waitcnt lgkmcnt(2)" ::: "memory"); else asm volatile("s_waitcnt lgkmcnt(0)" ::: "memory");
;   SBAR();
;   p0 = __builtin_amdgcn_mfma_f32_32x32x16_bf16(k0[D0 & 1], qr[D0], p0, 0, 0, 0);
;   p1 = __builtin_amdgcn_mfma_f32_32x32x16_bf16(k1[D0 & 1], qr[D0], p1, 0, 0, 0);
;   SBAR();
;   if constexpr (D0 + 1 < 8) qk_step<BUFOFF, (D0 + 1 < 8 ? D0 + 1 : 7)>(p0, p1, ka0, qr, k0, k1);
; }
; template <int BUFOFF> __device__ __forceinline__ void qkt_rolling(f32x16& p0, f32x16& p1, int ka0, const bf16x8 (&qr)[8]) {
;   bf16x8 k0[2], k1[2];
;   asm volatile("s_waitcnt lgkmcnt(0)" ::: "memory");
;   k0[0] = k_read<BUFOFF>(ka0); k1[0] = k_read<BUFOFF + 8192>(ka0);
;   qk_step<BUFOFF, 0>(p0, p1, ka0, qr, k0, k1);
; }
	v_mfma_f32_32x32x16_bf16 v[130:145], v[206:209], v[174:177], v[130:145]
	ds_read_b128 v[206:209], v243 offset:8192
	s_waitcnt lgkmcnt(3)
	v_mfma_f32_32x32x16_bf16 v[130:145], v[194:197], v[178:181], v[130:145]
	s_waitcnt lgkmcnt(2)
	v_mfma_f32_32x32x16_bf16 v[130:145], v[198:201], v[182:185], v[130:145]
	s_waitcnt lgkmcnt(1)
	v_mfma_f32_32x32x16_bf16 v[130:145], v[202:205], v[186:189], v[130:145]
	s_waitcnt lgkmcnt(0)
	v_mfma_f32_32x32x16_bf16 v[130:145], v[206:209], v[190:193], v[130:145]
	s_nop 10
	v_max_f32_e32 v0, v147, v147
	v_max_f32_e32 v194, v146, v146
	v_max_f32_e32 v0, v194, v0
	v_max3_f32 v0, v0, v148, v149
	v_max3_f32 v0, v0, v150, v151
	v_max3_f32 v0, v0, v152, v153
	v_max3_f32 v0, v0, v154, v155
	v_max3_f32 v0, v0, v156, v157
	v_max3_f32 v0, v0, v158, v159
	v_max3_f32 v0, v0, v160, v161
	v_max3_f32 v0, v0, v130, v131
	v_max3_f32 v0, v0, v132, v133
	v_max3_f32 v0, v0, v134, v135
	v_max3_f32 v0, v0, v136, v137
	v_max3_f32 v0, v0, v138, v139
	v_max3_f32 v0, v0, v140, v141
	v_max3_f32 v0, v0, v142, v143
	v_max3_f32 v0, v0, v144, v145
	v_mov_b32_e32 v194, v0
	s_nop 1
	v_permlane32_swap_b32_e32 v0, v194
	v_max_f32_e32 v194, v194, v194
	v_max_f32_e32 v0, v0, v0
	v_max_f32_e32 v0, v0, v194
	v_max_f32_e32 v195, v246, v246
	v_max_f32_e32 v247, v195, v0
	v_sub_f32_e32 v194, v0, v246
	v_sub_f32_e32 v0, v246, v247
	v_mul_f32_e32 v0, 0x3e0293ee, v0
	v_exp_f32_e32 v0, v0
	v_cmp_ge_f32_e32 vcc, s95, v194
	s_cmp_eq_u64 vcc, exec
	s_cselect_b64 s[6:7], -1, 0
	v_cndmask_b32_e64 v0, v0, 1.0, s[6:7]
	v_cmp_gt_f32_e32 vcc, 1.0, v0
	s_cbranch_vccz .LBB0_1440
	s_and_saveexec_b64 s[24:25], s[0:1]
	ds_write_b32 v237, v0 offset:128
	s_or_b64 exec, exec, s[24:25]
	s_waitcnt lgkmcnt(0)
	v_add_u32_e32 v194, s28, v212
	ds_read_b128 v[206:209], v194 offset:224
	ds_read_b128 v[202:205], v194 offset:192
	ds_read_b128 v[198:201], v194 offset:160
	ds_read_b128 v[194:197], v194 offset:128
	s_waitcnt lgkmcnt(0)
	v_pk_mul_f32 v[126:127], v[126:127], v[206:207]
	v_pk_mul_f32 v[122:123], v[122:123], v[202:203]
	v_pk_mul_f32 v[118:119], v[118:119], v[198:199]
	v_pk_mul_f32 v[128:129], v[128:129], v[208:209]
	v_pk_mul_f32 v[124:125], v[124:125], v[204:205]
	v_pk_mul_f32 v[120:121], v[120:121], v[200:201]
	v_pk_mul_f32 v[116:117], v[116:117], v[196:197]
	v_pk_mul_f32 v[114:115], v[114:115], v[194:195]
	v_pk_mul_f32 v[110:111], v[110:111], v[206:207]
	v_pk_mul_f32 v[106:107], v[106:107], v[202:203]
	v_pk_mul_f32 v[102:103], v[102:103], v[198:199]
	v_pk_mul_f32 v[112:113], v[112:113], v[208:209]
	v_pk_mul_f32 v[108:109], v[108:109], v[204:205]
	v_pk_mul_f32 v[104:105], v[104:105], v[200:201]
	v_pk_mul_f32 v[100:101], v[100:101], v[196:197]
	v_pk_mul_f32 v[98:99], v[98:99], v[194:195]
	v_pk_mul_f32 v[94:95], v[94:95], v[206:207]
	v_pk_mul_f32 v[90:91], v[90:91], v[202:203]
	v_pk_mul_f32 v[86:87], v[86:87], v[198:199]
	v_pk_mul_f32 v[96:97], v[96:97], v[208:209]
	v_pk_mul_f32 v[92:93], v[92:93], v[204:205]
	v_pk_mul_f32 v[88:89], v[88:89], v[200:201]
	v_pk_mul_f32 v[84:85], v[84:85], v[196:197]
	v_pk_mul_f32 v[82:83], v[82:83], v[194:195]
	v_pk_mul_f32 v[78:79], v[78:79], v[206:207]
	v_pk_mul_f32 v[74:75], v[74:75], v[202:203]
	v_pk_mul_f32 v[70:71], v[70:71], v[198:199]
	v_pk_mul_f32 v[80:81], v[80:81], v[208:209]
	v_pk_mul_f32 v[76:77], v[76:77], v[204:205]
	v_pk_mul_f32 v[72:73], v[72:73], v[200:201]
	v_pk_mul_f32 v[68:69], v[68:69], v[196:197]
	v_pk_mul_f32 v[66:67], v[66:67], v[194:195]
	v_pk_mul_f32 v[62:63], v[62:63], v[206:207]
	v_pk_mul_f32 v[58:59], v[58:59], v[202:203]
	v_pk_mul_f32 v[54:55], v[54:55], v[198:199]
	v_pk_mul_f32 v[64:65], v[64:65], v[208:209]
	v_pk_mul_f32 v[60:61], v[60:61], v[204:205]
	v_pk_mul_f32 v[56:57], v[56:57], v[200:201]
	v_pk_mul_f32 v[52:53], v[52:53], v[196:197]
	v_pk_mul_f32 v[50:51], v[50:51], v[194:195]
	v_pk_mul_f32 v[46:47], v[46:47], v[206:207]
	v_pk_mul_f32 v[42:43], v[42:43], v[202:203]
	v_pk_mul_f32 v[38:39], v[38:39], v[198:199]
	v_pk_mul_f32 v[48:49], v[48:49], v[208:209]
	v_pk_mul_f32 v[44:45], v[44:45], v[204:205]
	v_pk_mul_f32 v[40:41], v[40:41], v[200:201]
	v_pk_mul_f32 v[36:37], v[36:37], v[196:197]
	v_pk_mul_f32 v[34:35], v[34:35], v[194:195]
	v_pk_mul_f32 v[30:31], v[30:31], v[206:207]
	v_pk_mul_f32 v[26:27], v[26:27], v[202:203]
	v_pk_mul_f32 v[22:23], v[22:23], v[198:199]
	v_pk_mul_f32 v[32:33], v[32:33], v[208:209]
	v_pk_mul_f32 v[28:29], v[28:29], v[204:205]
	v_pk_mul_f32 v[24:25], v[24:25], v[200:201]
	v_pk_mul_f32 v[20:21], v[20:21], v[196:197]
	v_pk_mul_f32 v[18:19], v[18:19], v[194:195]
	v_pk_mul_f32 v[14:15], v[14:15], v[206:207]
	v_pk_mul_f32 v[10:11], v[10:11], v[202:203]
	v_pk_mul_f32 v[6:7], v[6:7], v[198:199]
	v_pk_mul_f32 v[16:17], v[16:17], v[208:209]
	v_pk_mul_f32 v[12:13], v[12:13], v[204:205]
	v_pk_mul_f32 v[8:9], v[8:9], v[200:201]
	v_pk_mul_f32 v[4:5], v[4:5], v[196:197]
	v_pk_mul_f32 v[2:3], v[2:3], v[194:195]
; __device__ __forceinline__ void partialSM(f32x16& p0, f32x16& p1, float& m_reg, float& mn, float& alpha) {
;     ...
;   float mnC = -mn * C;
; #pragma unroll
;   for (int r = 0; r < 16; ++r) p0[r] = fmaf(p0[r], C, mnC);
; #pragma unroll
;   for (int r = 0; r < 16; ++r) p1[r] = fmaf(p1[r], C, mnC);
; #pragma unroll
;   for (int r = 0; r < 16; ++r) p0[r] = __builtin_amdgcn_exp2f(p0[r]);
; }
; __device__ __forceinline__ void finishSM(f32x16& p0, f32x16& p1, float alpha, float& l_reg, bf16x8& pa0, bf16x8& pa1, bf16x8& pa2, bf16x8& pa3) {
; #pragma unroll
;   for (int r = 0; r < 16; ++r) p1[r] = __builtin_amdgcn_exp2f(p1[r]);
;   float ps = 0;
; #pragma unroll
;   for (int r = 0; r < 16; ++r) ps += p0[r];
; #pragma unroll
;   for (int r = 0; r < 16; ++r) ps += p1[r];
;   { auto rr = __builtin_amdgcn_permlane32_swap(__float_as_uint(ps), __float_as_uint(ps), false, false);
;     ps = __uint_as_float(rr[0]) + __uint_as_float(rr[1]); }
;   l_reg = l_reg * alpha + ps;
;     ...
;   PK4(p0, 0, pa0); PK4(p0, 8, pa1); PK4(p1, 0, pa2); PK4(p1, 8, pa3);
.LBB0_1440:
	v_cndmask_b32_e64 v246, v247, v246, s[6:7]
	v_mul_f32_e32 v194, 0xbe0293ee, v246
	v_fmamk_f32 v146, v146, 0x3e0293ee, v194
	v_fmamk_f32 v147, v147, 0x3e0293ee, v194
	v_fmamk_f32 v148, v148, 0x3e0293ee, v194
	v_fmamk_f32 v149, v149, 0x3e0293ee, v194
	v_fmamk_f32 v150, v150, 0x3e0293ee, v194
	v_fmamk_f32 v151, v151, 0x3e0293ee, v194
	v_fmamk_f32 v152, v152, 0x3e0293ee, v194
	v_fmamk_f32 v153, v153, 0x3e0293ee, v194
	v_fmamk_f32 v154, v154, 0x3e0293ee, v194
	v_fmamk_f32 v155, v155, 0x3e0293ee, v194
	v_fmamk_f32 v156, v156, 0x3e0293ee, v194
	v_fmamk_f32 v157, v157, 0x3e0293ee, v194
	v_fmamk_f32 v158, v158, 0x3e0293ee, v194
	v_fmamk_f32 v159, v159, 0x3e0293ee, v194
	v_fmamk_f32 v160, v160, 0x3e0293ee, v194
	v_fmamk_f32 v161, v161, 0x3e0293ee, v194
	v_fmamk_f32 v130, v130, 0x3e0293ee, v194
	v_fmamk_f32 v131, v131, 0x3e0293ee, v194
	v_fmamk_f32 v132, v132, 0x3e0293ee, v194
	v_fmamk_f32 v133, v133, 0x3e0293ee, v194
	v_fmamk_f32 v134, v134, 0x3e0293ee, v194
	v_fmamk_f32 v135, v135, 0x3e0293ee, v194
	v_fmamk_f32 v136, v136, 0x3e0293ee, v194
	v_fmamk_f32 v137, v137, 0x3e0293ee, v194
	v_fmamk_f32 v138, v138, 0x3e0293ee, v194
	v_fmamk_f32 v139, v139, 0x3e0293ee, v194
	v_fmamk_f32 v140, v140, 0x3e0293ee, v194
	v_fmamk_f32 v141, v141, 0x3e0293ee, v194
	v_fmamk_f32 v142, v142, 0x3e0293ee, v194
	v_fmamk_f32 v143, v143, 0x3e0293ee, v194
	v_fmamk_f32 v144, v144, 0x3e0293ee, v194
	v_fmac_f32_e32 v194, 0x3e0293ee, v145
	v_exp_f32_e32 v145, v146
	v_exp_f32_e32 v146, v147
	v_exp_f32_e32 v147, v148
	v_exp_f32_e32 v148, v149
	v_exp_f32_e32 v149, v150
	v_exp_f32_e32 v150, v151
	v_exp_f32_e32 v151, v152
	v_exp_f32_e32 v152, v153
	v_exp_f32_e32 v153, v154
	v_exp_f32_e32 v154, v155
	v_exp_f32_e32 v155, v156
	v_exp_f32_e32 v156, v157
	v_exp_f32_e32 v157, v158
	v_exp_f32_e32 v158, v159
	v_exp_f32_e32 v159, v160
	v_exp_f32_e32 v160, v161
	v_exp_f32_e32 v161, v130
	v_add_f32_e32 v130, 0, v145
	v_add_f32_e32 v130, v146, v130
	v_add_f32_e32 v130, v147, v130
	v_add_f32_e32 v130, v148, v130
	v_add_f32_e32 v130, v149, v130
	v_add_f32_e32 v130, v150, v130
	v_add_f32_e32 v130, v151, v130
	v_add_f32_e32 v130, v152, v130
	v_add_f32_e32 v130, v153, v130
	v_add_f32_e32 v130, v154, v130
	v_add_f32_e32 v130, v155, v130
	v_add_f32_e32 v130, v156, v130
	v_add_f32_e32 v130, v157, v130
	v_exp_f32_e32 v195, v131
	v_add_f32_e32 v130, v158, v130
	v_exp_f32_e32 v196, v132
	v_add_f32_e32 v130, v159, v130
	v_exp_f32_e32 v197, v133
	v_add_f32_e32 v130, v160, v130
	v_exp_f32_e32 v198, v134
	v_add_f32_e32 v130, v161, v130
	v_exp_f32_e32 v199, v135
	v_add_f32_e32 v130, v195, v130
	v_exp_f32_e32 v200, v136
	v_add_f32_e32 v130, v196, v130
	v_exp_f32_e32 v201, v137
	v_add_f32_e32 v130, v197, v130
	v_exp_f32_e32 v202, v138
	v_add_f32_e32 v130, v198, v130
	v_exp_f32_e32 v203, v139
	v_add_f32_e32 v130, v199, v130
	v_exp_f32_e32 v204, v140
	v_add_f32_e32 v130, v200, v130
	v_exp_f32_e32 v205, v141
	v_add_f32_e32 v130, v201, v130
	v_exp_f32_e32 v206, v142
	v_add_f32_e32 v130, v202, v130
	v_exp_f32_e32 v207, v143
	v_add_f32_e32 v130, v203, v130
	v_exp_f32_e32 v208, v144
	v_add_f32_e32 v130, v204, v130
	v_exp_f32_e32 v194, v194
	v_add_f32_e32 v130, v205, v130
	v_add_f32_e32 v130, v206, v130
	v_add_f32_e32 v130, v207, v130
	v_add_f32_e32 v130, v208, v130
	v_add_f32_e32 v247, v194, v130
	v_mov_b32_e32 v248, v247
	s_nop 1
	v_permlane32_swap_b32_e32 v247, v248
	v_cvt_pk_bf16_f32 v130, v145, v146
	v_cvt_pk_bf16_f32 v131, v147, v148
	v_cvt_pk_bf16_f32 v132, v149, v150
	v_cvt_pk_bf16_f32 v133, v151, v152
	v_cvt_pk_bf16_f32 v134, v153, v154
	v_cvt_pk_bf16_f32 v135, v155, v156
	v_cvt_pk_bf16_f32 v136, v157, v158
	v_cvt_pk_bf16_f32 v137, v159, v160
	v_cvt_pk_bf16_f32 v138, v161, v195
	v_cvt_pk_bf16_f32 v139, v196, v197
	v_cvt_pk_bf16_f32 v140, v198, v199
	v_cvt_pk_bf16_f32 v141, v200, v201
	v_cvt_pk_bf16_f32 v142, v202, v203
	v_cvt_pk_bf16_f32 v143, v204, v205
	v_cvt_pk_bf16_f32 v144, v206, v207
	v_cvt_pk_bf16_f32 v145, v208, v194
	s_nop 0
	v_permlane32_swap_b32_e32 v130, v132
	v_permlane32_swap_b32_e32 v131, v133
	v_permlane32_swap_b32_e32 v134, v136
	v_permlane32_swap_b32_e32 v135, v137
	v_permlane32_swap_b32_e32 v138, v140
	v_permlane32_swap_b32_e32 v139, v141
	v_permlane32_swap_b32_e32 v142, v144
	v_permlane32_swap_b32_e32 v143, v145
	s_waitcnt vmcnt(0)
	s_barrier
; #define SBAR() __builtin_amdgcn_sched_barrier(0)
; template <int I> __device__ __forceinline__ void pv_step(f32x16* o, int vb, const bf16x8 (&pa)[4], s16x4 (&l)[3], s16x4 (&h)[3]) {
;   if constexpr (I + 2 < 32) pv_rd<(I + 2 < 32 ? I + 2 : 0)>(vb, l[(I + 2) % 3], h[(I + 2) % 3]);
;   if constexpr (I + 2 < 32) asm volatile("s_waitcnt lgkmcnt(4)" ::: "memory"); else if constexpr (I + 1 < 32) asm volatile("s_waitcnt lgkmcnt(2)" ::: "memory"); else asm volatile("s_waitcnt lgkmcnt(0)" ::: "memory");
;   SBAR();
;   const s16x4 L = l[I % 3], H = h[I % 3];
;   o[I >> 2] = __builtin_amdgcn_mfma_f32_32x32x16_bf16(pa[I & 3], (bf16x8){L[0], L[1], L[2], L[3], H[0], H[1], H[2], H[3]}, o[I >> 2], 0, 0, 0);
;   SBAR();
;   if constexpr (I + 1 < 32) pv_step<(I + 1 < 32 ? I + 1 : 31)>(o, vb, pa, l, h);
; }
; __device__ __forceinline__ void pv_all_rolling(f32x16* o, int vb, bf16x8 pa0, bf16x8 pa1, bf16x8 pa2, bf16x8 pa3) {
;   const bf16x8 pa[4] = {pa0, pa1, pa2, pa3}; s16x4 l[3], h[3];
;   asm volatile("s_waitcnt lgkmcnt(0)" ::: "memory");
;   pv_rd<0>(vb, l[0], h[0]); pv_rd<1>(vb, l[1], h[1]);
;   pv_step<0>(o, vb, pa, l, h);
	s_setprio 0
	s_waitcnt lgkmcnt(0)
	ds_read_b64_tr_b16 v[146:147], v213 offset:0
	ds_read_b64_tr_b16 v[148:149], v213 offset:2048
	ds_read_b64_tr_b16 v[150:151], v213 offset:4096
	ds_read_b64_tr_b16 v[152:153], v213 offset:6144
	ds_read_b64_tr_b16 v[154:155], v213 offset:8192
	ds_read_b64_tr_b16 v[156:157], v213 offset:10240
	ds_read_b64_tr_b16 v[158:159], v213 offset:12288
	ds_read_b64_tr_b16 v[160:161], v213 offset:14336
	ds_read_b64_tr_b16 v[194:195], v213 offset:512
	ds_read_b64_tr_b16 v[196:197], v213 offset:2560
	ds_read_b64_tr_b16 v[198:199], v213 offset:4608
	ds_read_b64_tr_b16 v[200:201], v213 offset:6656
	ds_read_b64_tr_b16 v[202:203], v213 offset:8704
	ds_read_b64_tr_b16 v[204:205], v213 offset:10752
	v_lshl_add_u64 v[232:233], v[218:219], 0, s[22:23]
	v_lshl_add_u64 v[232:233], v[232:233], 0, s[10:11]
	s_add_i32 m0, s62, 0x8000
	s_nop 0
	global_load_lds_dwordx4 v[232:233], off
	s_waitcnt lgkmcnt(12)
	s_nop 0
	v_mfma_f32_32x32x16_bf16 v[114:129], v[130:133], v[146:149], v[114:129]
	ds_read_b64_tr_b16 v[206:207], v213 offset:12800
	ds_read_b64_tr_b16 v[208:209], v213 offset:14848
	v_lshl_add_u64 v[232:233], v[218:219], 0, s[22:23]
	v_lshl_add_u64 v[232:233], v[232:233], 0, s[12:13]
	s_add_i32 m0, s62, 0xc000
	s_nop 0
	global_load_lds_dwordx4 v[232:233], off
	s_waitcnt lgkmcnt(12)
	v_mfma_f32_32x32x16_bf16 v[114:129], v[134:137], v[150:153], v[114:129]
	ds_read_b64_tr_b16 v[146:147], v213 offset:1024
	ds_read_b64_tr_b16 v[148:149], v213 offset:3072
	v_lshl_add_u64 v[232:233], v[220:221], 0, s[22:23]
	v_lshl_add_u64 v[232:233], v[232:233], 0, s[10:11]
	s_add_i32 m0, s62, 0x8400
	s_nop 0
	global_load_lds_dwordx4 v[232:233], off
	s_waitcnt lgkmcnt(12)
	v_mfma_f32_32x32x16_bf16 v[114:129], v[138:141], v[154:157], v[114:129]
	ds_read_b64_tr_b16 v[150:151], v213 offset:5120
	ds_read_b64_tr_b16 v[152:153], v213 offset:7168
	v_lshl_add_u64 v[232:233], v[220:221], 0, s[22:23]
	v_lshl_add_u64 v[232:233], v[232:233], 0, s[12:13]
	s_add_i32 m0, s62, 0xc400
	s_nop 0
	global_load_lds_dwordx4 v[232:233], off
	s_waitcnt lgkmcnt(12)
	v_mfma_f32_32x32x16_bf16 v[114:129], v[142:145], v[158:161], v[114:129]
	ds_read_b64_tr_b16 v[154:155], v213 offset:9216
	ds_read_b64_tr_b16 v[156:157], v213 offset:11264
	s_waitcnt lgkmcnt(12)
	v_mfma_f32_32x32x16_bf16 v[98:113], v[130:133], v[194:197], v[98:113]
	ds_read_b64_tr_b16 v[158:159], v213 offset:13312
	ds_read_b64_tr_b16 v[160:161], v213 offset:15360
	s_waitcnt lgkmcnt(12)
	v_mfma_f32_32x32x16_bf16 v[98:113], v[134:137], v[198:201], v[98:113]
	ds_read_b64_tr_b16 v[194:195], v213 offset:1536
	ds_read_b64_tr_b16 v[196:197], v213 offset:3584
	s_waitcnt lgkmcnt(12)
	v_mfma_f32_32x32x16_bf16 v[98:113], v[138:141], v[202:205], v[98:113]
	ds_read_b64_tr_b16 v[198:199], v213 offset:5632
	ds_read_b64_tr_b16 v[200:201], v213 offset:7680
	s_waitcnt lgkmcnt(12)
	v_mfma_f32_32x32x16_bf16 v[98:113], v[142:145], v[206:209], v[98:113]
	ds_read_b64_tr_b16 v[202:203], v213 offset:9728
	ds_read_b64_tr_b16 v[204:205], v213 offset:11776
	s_waitcnt lgkmcnt(12)
	v_mfma_f32_32x32x16_bf16 v[82:97], v[130:133], v[146:149], v[82:97]
	ds_read_b64_tr_b16 v[206:207], v213 offset:13824
	ds_read_b64_tr_b16 v[208:209], v213 offset:15872
	s_waitcnt lgkmcnt(12)
	v_mfma_f32_32x32x16_bf16 v[82:97], v[134:137], v[150:153], v[82:97]
	ds_read_b64_tr_b16 v[146:147], v213 offset:16384
	ds_read_b64_tr_b16 v[148:149], v213 offset:18432
	s_waitcnt lgkmcnt(12)
	v_mfma_f32_32x32x16_bf16 v[82:97], v[138:141], v[154:157], v[82:97]
	ds_read_b64_tr_b16 v[150:151], v213 offset:20480
	ds_read_b64_tr_b16 v[152:153], v213 offset:22528
	s_waitcnt lgkmcnt(12)
	v_mfma_f32_32x32x16_bf16 v[82:97], v[142:145], v[158:161], v[82:97]
	ds_read_b64_tr_b16 v[154:155], v213 offset:24576
	ds_read_b64_tr_b16 v[156:157], v213 offset:26624
	s_waitcnt lgkmcnt(12)
	v_mfma_f32_32x32x16_bf16 v[66:81], v[130:133], v[194:197], v[66:81]
	ds_read_b64_tr_b16 v[158:159], v213 offset:28672
	ds_read_b64_tr_b16 v[160:161], v213 offset:30720
	s_waitcnt lgkmcnt(12)
	v_mfma_f32_32x32x16_bf16 v[66:81], v[134:137], v[198:201], v[66:81]
	ds_read_b64_tr_b16 v[194:195], v213 offset:16896
	ds_read_b64_tr_b16 v[196:197], v213 offset:18944
	s_waitcnt lgkmcnt(12)
	v_mfma_f32_32x32x16_bf16 v[66:81], v[138:141], v[202:205], v[66:81]
	ds_read_b64_tr_b16 v[198:199], v213 offset:20992
	ds_read_b64_tr_b16 v[200:201], v213 offset:23040
	s_waitcnt lgkmcnt(12)
	v_mfma_f32_32x32x16_bf16 v[66:81], v[142:145], v[206:209], v[66:81]
	ds_read_b64_tr_b16 v[202:203], v213 offset:25088
	ds_read_b64_tr_b16 v[204:205], v213 offset:27136
	s_waitcnt lgkmcnt(12)
	v_mfma_f32_32x32x16_bf16 v[50:65], v[130:133], v[146:149], v[50:65]
	ds_read_b64_tr_b16 v[206:207], v213 offset:29184
	ds_read_b64_tr_b16 v[208:209], v213 offset:31232
	s_waitcnt lgkmcnt(12)
	v_mfma_f32_32x32x16_bf16 v[50:65], v[134:137], v[150:153], v[50:65]
	ds_read_b64_tr_b16 v[146:147], v213 offset:17408
	ds_read_b64_tr_b16 v[148:149], v213 offset:19456
	s_waitcnt lgkmcnt(12)
	v_mfma_f32_32x32x16_bf16 v[50:65], v[138:141], v[154:157], v[50:65]
	ds_read_b64_tr_b16 v[150:151], v213 offset:21504
	ds_read_b64_tr_b16 v[152:153], v213 offset:23552
	s_waitcnt lgkmcnt(12)
	v_mfma_f32_32x32x16_bf16 v[50:65], v[142:145], v[158:161], v[50:65]
	ds_read_b64_tr_b16 v[154:155], v213 offset:25600
	ds_read_b64_tr_b16 v[156:157], v213 offset:27648
	s_waitcnt lgkmcnt(12)
	v_mfma_f32_32x32x16_bf16 v[34:49], v[130:133], v[194:197], v[34:49]
	ds_read_b64_tr_b16 v[158:159], v213 offset:29696
	ds_read_b64_tr_b16 v[160:161], v213 offset:31744
	s_waitcnt lgkmcnt(12)
	v_mfma_f32_32x32x16_bf16 v[34:49], v[134:137], v[198:201], v[34:49]
	ds_read_b64_tr_b16 v[194:195], v213 offset:17920
	ds_read_b64_tr_b16 v[196:197], v213 offset:19968
	s_waitcnt lgkmcnt(12)
	v_mfma_f32_32x32x16_bf16 v[34:49], v[138:141], v[202:205], v[34:49]
	ds_read_b64_tr_b16 v[198:199], v213 offset:22016
	ds_read_b64_tr_b16 v[200:201], v213 offset:24064
	s_waitcnt lgkmcnt(12)
	v_mfma_f32_32x32x16_bf16 v[34:49], v[142:145], v[206:209], v[34:49]
	ds_read_b64_tr_b16 v[202:203], v213 offset:26112
	ds_read_b64_tr_b16 v[204:205], v213 offset:28160
	s_waitcnt lgkmcnt(12)
	v_mfma_f32_32x32x16_bf16 v[18:33], v[130:133], v[146:149], v[18:33]
	ds_read_b64_tr_b16 v[206:207], v213 offset:30208
	ds_read_b64_tr_b16 v[208:209], v213 offset:32256
	s_waitcnt lgkmcnt(12)
	v_mfma_f32_32x32x16_bf16 v[18:33], v[134:137], v[150:153], v[18:33]
	s_waitcnt lgkmcnt(10)
	v_mfma_f32_32x32x16_bf16 v[18:33], v[138:141], v[154:157], v[18:33]
	s_waitcnt lgkmcnt(8)
	v_mfma_f32_32x32x16_bf16 v[18:33], v[142:145], v[158:161], v[18:33]
	s_waitcnt lgkmcnt(6)
	v_mfma_f32_32x32x16_bf16 v[2:17], v[130:133], v[194:197], v[2:17]
	s_waitcnt lgkmcnt(4)
	v_mfma_f32_32x32x16_bf16 v[2:17], v[134:137], v[198:201], v[2:17]
	s_waitcnt lgkmcnt(2)
	v_mfma_f32_32x32x16_bf16 v[2:17], v[138:141], v[202:205], v[2:17]
	s_waitcnt lgkmcnt(0)
	v_mfma_f32_32x32x16_bf16 v[2:17], v[142:145], v[206:209], v[2:17]
	s_waitcnt vmcnt(0)
	s_cmp_ge_u32 s80, s96
	s_cselect_b64 s[24:25], -1, 0
	s_and_b64 vcc, exec, s[24:25]
	s_waitcnt vmcnt(0) lgkmcnt(0)
	s_barrier
; #define SBAR() __builtin_amdgcn_sched_barrier(0)
; template <int OFF> __device__ __forceinline__ bf16x8 k_read(int a) { bf16x8 r; asm volatile("ds_read_b128 %0, %1 offset:%2" : "=&v"(r) : "v"(a), "i"(OFF) : "memory"); return r; }
; __device__ __forceinline__ void partialSM(f32x16& p0, f32x16& p1, float& m_reg, float& mn, float& alpha) {
;   constexpr float C = SCALE * 1.4426950408889634f;
;   float pmax = p0[0];
; #pragma unroll
;   for (int r = 1; r < 16; ++r) pmax = fmaxf(pmax, p0[r]);
; #pragma unroll
;   for (int r = 0; r < 16; ++r) pmax = fmaxf(pmax, p1[r]);
;   { auto rr = __builtin_amdgcn_permlane32_swap(__float_as_uint(pmax), __float_as_uint(pmax), false, false);
;     pmax = fmaxf(__uint_as_float(rr[0]), __uint_as_float(rr[1])); }
;   if (__builtin_expect(__all(pmax - m_reg <= THR / SCALE), 1)) { mn = m_reg; alpha = 1.f; }
;   else { mn = fmaxf(m_reg, pmax); alpha = __builtin_amdgcn_exp2f((m_reg - mn) * C); m_reg = mn; }
; template <int BUFOFF, int D0> __device__ __forceinline__ void qk_step(f32x16& p0, f32x16& p1, int ka0, const bf16x8 (&qr)[8], bf16x8 (&k0)[2], bf16x8 (&k1)[2]) {
;   if constexpr (D0 + 1 < 8) { const int a_ = ka0 ^ ((D0 + 1) << 5); k0[(D0 + 1) & 1] = k_read<BUFOFF>(a_); k1[(D0 + 1) & 1] = k_read<BUFOFF + 8192>(a_); }
;   if constexpr (D0 + 1 < 8) asm volatile("s_waitcnt lgkmcnt(2)" ::: "memory"); else asm volatile("s_waitcnt lgkmcnt(0)" ::: "memory");
;   SBAR();
;   p0 = __builtin_amdgcn_mfma_f32_32x32x16_bf16(k0[D0 & 1], qr[D0], p0, 0, 0, 0);
;   p1 = __builtin_amdgcn_mfma_f32_32x32x16_bf16(k1[D0 & 1], qr[D0], p1, 0, 0, 0);
;   SBAR();
;   if constexpr (D0 + 1 < 8) qk_step<BUFOFF, (D0 + 1 < 8 ? D0 + 1 : 7)>(p0, p1, ka0, qr, k0, k1);
; }
; template <int BUFOFF> __device__ __forceinline__ void qkt_rolling(f32x16& p0, f32x16& p1, int ka0, const bf16x8 (&qr)[8]) {
;   bf16x8 k0[2], k1[2];
;   asm volatile("s_waitcnt lgkmcnt(0)" ::: "memory");
;   k0[0] = k_read<BUFOFF>(ka0); k1[0] = k_read<BUFOFF + 8192>(ka0);
;   qk_step<BUFOFF, 0>(p0, p1, ka0, qr, k0, k1);
; }
.LBB0_1442:
	s_setprio 1
	s_waitcnt lgkmcnt(0)
	ds_read_b128 v[194:197], v235 offset:16384
	ds_read_b128 v[198:201], v236 offset:16384
	ds_read_b128 v[202:205], v238 offset:16384
	ds_read_b128 v[206:209], v239 offset:16384
	ds_read_b128 v[130:133], v240 offset:16384
	ds_read_b128 v[134:137], v241 offset:16384
	ds_read_b128 v[138:141], v242 offset:16384
	ds_read_b128 v[142:145], v243 offset:16384
	v_lshl_add_u64 v[232:233], v[224:225], 0, s[14:15]
	s_mov_b32 m0, s61
	s_nop 0
	global_load_lds_dwordx4 v[232:233], off
	v_lshl_add_u64 v[232:233], v[228:229], 0, s[14:15]
	s_mov_b32 m0, s67
	s_nop 0
	global_load_lds_dwordx4 v[232:233], off
	s_waitcnt lgkmcnt(7)
	s_nop 0
	v_mfma_f32_32x32x16_bf16 v[146:161], v[194:197], v[162:165], 0
	ds_read_b128 v[194:197], v235 offset:24576
	s_waitcnt lgkmcnt(7)
	v_mfma_f32_32x32x16_bf16 v[146:161], v[198:201], v[166:169], v[146:161]
	ds_read_b128 v[198:201], v236 offset:24576
	s_waitcnt lgkmcnt(7)
	v_mfma_f32_32x32x16_bf16 v[146:161], v[202:205], v[170:173], v[146:161]
	ds_read_b128 v[202:205], v238 offset:24576
	s_waitcnt lgkmcnt(7)
	v_mfma_f32_32x32x16_bf16 v[146:161], v[206:209], v[174:177], v[146:161]
	ds_read_b128 v[206:209], v239 offset:24576
	s_waitcnt lgkmcnt(7)
	v_mfma_f32_32x32x16_bf16 v[146:161], v[130:133], v[178:181], v[146:161]
	s_waitcnt lgkmcnt(6)
	v_mfma_f32_32x32x16_bf16 v[146:161], v[134:137], v[182:185], v[146:161]
	s_waitcnt lgkmcnt(5)
	v_mfma_f32_32x32x16_bf16 v[146:161], v[138:141], v[186:189], v[146:161]
	s_waitcnt lgkmcnt(4)
	v_mfma_f32_32x32x16_bf16 v[146:161], v[142:145], v[190:193], v[146:161]
	s_waitcnt lgkmcnt(3)
	v_mfma_f32_32x32x16_bf16 v[130:145], v[194:197], v[162:165], 0
	ds_read_b128 v[194:197], v240 offset:24576
	s_waitcnt lgkmcnt(3)
	v_mfma_f32_32x32x16_bf16 v[130:145], v[198:201], v[166:169], v[130:145]
	ds_read_b128 v[198:201], v241 offset:24576
	s_waitcnt lgkmcnt(3)
	v_mfma_f32_32x32x16_bf16 v[130:145], v[202:205], v[170:173], v[130:145]
	ds_read_b128 v[202:205], v242 offset:24576
	s_waitcnt lgkmcnt(3)
	v_mfma_f32_32x32x16_bf16 v[130:145], v[206:209], v[174:177], v[130:145]
	ds_read_b128 v[206:209], v243 offset:24576
	s_waitcnt lgkmcnt(3)
	v_mfma_f32_32x32x16_bf16 v[130:145], v[194:197], v[178:181], v[130:145]
	s_waitcnt lgkmcnt(2)
	v_mfma_f32_32x32x16_bf16 v[130:145], v[198:201], v[182:185], v[130:145]
	s_waitcnt lgkmcnt(1)
	v_mfma_f32_32x32x16_bf16 v[130:145], v[202:205], v[186:189], v[130:145]
	s_waitcnt lgkmcnt(0)
	v_mfma_f32_32x32x16_bf16 v[130:145], v[206:209], v[190:193], v[130:145]
	s_nop 10
	v_max_f32_e32 v194, v147, v147
	v_max_f32_e32 v195, v146, v146
	v_max_f32_e32 v194, v195, v194
	v_max3_f32 v194, v194, v148, v149
	v_max3_f32 v194, v194, v150, v151
	v_max3_f32 v194, v194, v152, v153
	v_max3_f32 v194, v194, v154, v155
	v_max3_f32 v194, v194, v156, v157
	v_max3_f32 v194, v194, v158, v159
	v_max3_f32 v194, v194, v160, v161
	v_max3_f32 v194, v194, v130, v131
	v_max3_f32 v194, v194, v132, v133
	v_max3_f32 v194, v194, v134, v135
	v_max3_f32 v194, v194, v136, v137
	v_max3_f32 v194, v194, v138, v139
	v_max3_f32 v194, v194, v140, v141
	v_max3_f32 v194, v194, v142, v143
	v_max3_f32 v194, v194, v144, v145
	v_mov_b32_e32 v195, v194
	s_nop 1
	v_permlane32_swap_b32_e32 v194, v195
	v_max_f32_e32 v195, v195, v195
	v_max_f32_e32 v194, v194, v194
	v_max_f32_e32 v194, v194, v195
	v_sub_f32_e32 v195, v194, v246
	v_cmp_ge_f32_e32 vcc, s95, v195
	v_max_f32_e32 v195, v246, v246
	v_max_f32_e32 v223, v195, v194
	v_sub_f32_e32 v194, v246, v223
	v_mul_f32_e32 v194, 0x3e0293ee, v194
	v_exp_f32_e32 v194, v194
	s_cmp_eq_u64 vcc, exec
	s_cselect_b64 s[6:7], -1, 0
	v_cndmask_b32_e64 v222, v194, 1.0, s[6:7]
	v_cmp_gt_f32_e32 vcc, 1.0, v222
	s_cbranch_vccz .LBB0_1435
	s_and_saveexec_b64 s[56:57], s[0:1]
	s_cbranch_execz .LBB0_1434
	ds_write_b32 v237, v222 offset:128
	s_branch .LBB0_1434
.LBB0_1445:
	s_setprio 0
	s_cmp_lt_u32 s29, 0x2000
	s_cbranch_scc0 .Lda_l1_lag_out
	s_barrier
